# static s_setprio 1 for waves 4-7 at kernel entry, all K-loop setprio toggles removed (on top of MFMA pair order + saddr DMA)
# baseline (speedup 1.0000x reference)
; #define LAS __attribute__((address_space(3)))
; __global__ void __launch_bounds__(NTHR, 2) fwd_megakernel(Params p) {
;     extern __shared__ __attribute__((aligned(16))) unsigned char lds_raw[];
;     LAS unsigned char* lds = (LAS unsigned char*)lds_raw;
;     cg::grid_group grid = cg::this_grid();
;     const int tid = threadIdx.x, lane = tid & 63, wave = __builtin_amdgcn_readfirstlane(tid >> 6), fr = lane & 15, fq = lane >> 4;
;     const int bx = blockIdx.x, G = gridDim.x;
;     const int gw = bx * 8 + wave, NGW = G * 8;
;     const size_t gtid = (size_t)bx * NTHR + tid, NGT = (size_t)G * NTHR;
;     unsigned char* ws = p.ws;
;     volatile LAS unsigned* xst = (volatile LAS unsigned*)(lds + 133120);
;     if (tid < 2) xst[tid] = 0u;
;     __syncthreads();
;     XcdBarrier xbar = xcd_barrier_post((unsigned*)(ws + WS_BAR), xst);
_Z14fwd_megakernel6Params:
	s_load_dword s19, s[0:1], 0xd8
	s_load_dwordx4 s[24:27], s[0:1], 0xc0
	s_load_dwordx2 s[20:21], s[0:1], 0xd0
	s_add_u32 s6, s0, 0xd0
	v_and_b32_e32 v184, 0x3ff, v0
	s_addc_u32 s7, s1, 0
	v_readfirstlane_b32 s3, v184
	v_mov_b32_e32 v185, 0
	v_cmp_gt_u32_e32 vcc, 2, v184
	v_writelane_b32 v251, s3, 0
	s_cmp_lt_u32 s3, 0x100
	s_cbranch_scc1 .Lprio_skip
	s_setprio 1
.Lprio_skip:
	s_and_saveexec_b64 s[4:5], vcc
	v_lshl_add_u32 v1, v184, 2, 0
	v_add_u32_e32 v1, 0x20800, v1
	ds_write_b32 v1, v185
	s_or_b64 exec, exec, s[4:5]
	s_waitcnt lgkmcnt(0)
	s_barrier
	s_getreg_b32 s3, hwreg(HW_REG_XCC_ID, 0, 4)
	s_and_b32 s18, s3, 15
	v_cmp_eq_u32_e64 s[22:23], 0, v184
	s_and_saveexec_b64 s[4:5], s[22:23]
	s_cbranch_execz .LBB0_5
	s_mov_b64 s[8:9], exec
	v_mbcnt_lo_u32_b32 v1, s8, 0
	v_mbcnt_hi_u32_b32 v1, s9, v1
	v_cmp_eq_u32_e32 vcc, 0, v1
	s_and_b64 s[10:11], exec, vcc
	s_mov_b64 exec, s[10:11]
	s_cbranch_execz .LBB0_5
	s_lshl_b32 s3, s18, 8
	s_bcnt1_i32_b64 s8, s[8:9]
	v_mov_b32_e32 v1, s3
	v_mov_b32_e32 v2, s8
	global_atomic_add v1, v2, s[26:27] offset:1024

; #define PG8_STAGE(bufoff, gbase, voff) do { _Pragma("unroll") for (int _i = 0; _i < 2; ++_i) \
;         __builtin_amdgcn_global_load_lds((const unsigned*)((const char*)(gbase) + (voff)[_i]), (LAS unsigned*)(lds + (bufoff) + ldsw + _i * 8192), 16, 0, 0); } while (0)
; #define PG8_LDA(dst, b, h) do { _Pragma("unroll") for (int m = 0; m < 4; ++m) _Pragma("unroll") for (int k = 0; k < 2; ++k) dst[m][k] = *(const LAS bf16x8*)(lds + PG8_SA(b, h) + aoff + m * 2048 + k * 1024); } while (0)
; #define PG8_LDB(dst, b, h) do { _Pragma("unroll") for (int n = 0; n < 2; ++n) _Pragma("unroll") for (int k = 0; k < 2; ++k) dst[n][k] = *(const LAS bf16x8*)(lds + PG8_SB(b, h) + boff + n * 2048 + k * 1024); } while (0)
; #define PG8_MMA(ai, bj, At, Bt) do { __builtin_amdgcn_s_setprio(1); _Pragma("unroll") for (int m = 0; m < 4; ++m) _Pragma("unroll") for (int n = 0; n < 2; ++n) _Pragma("unroll") for (int k = 0; k < 2; ++k) \
;         acc[ai][bj][m][n] = __builtin_amdgcn_mfma_f32_16x16x32_bf16(Bt[n][k], At[m][k], acc[ai][bj][m][n], 0, 0, 0); __builtin_amdgcn_s_setprio(0); } while (0)
; #define PG8_WAIT_V(n) asm volatile("s_waitcnt vmcnt(" #n ")" ::: "memory")
; #define PG8_WAIT_L(n) asm volatile("s_waitcnt lgkmcnt(" #n ")" ::: "memory")
; #define PG8_BAR __builtin_amdgcn_s_barrier()
; #define PG8_SCHED __builtin_amdgcn_sched_barrier(0)
; template <bool ALIGN_EPI, class Epi, class Sched>
; __device__ __forceinline__ void gemm_phase(LAS unsigned char* lds, const int lda, const int ldb, const int K, const Sched& S, const Epi& E, const size_t kstepA = (size_t)(BK * 2), const size_t kstepB = (size_t)(BK * 2)) {
;     ...
;             const char* a1 = cA + (size_t)(t + 1) * kstepA;
;             const char* a2 = last ? nA : cA + (size_t)(t + 2) * kstepA; const char* b2 = last ? nB : cB + (size_t)(t + 2) * kstep;
;             const char* a3 = a2 + kstepA; const char* b3 = b2 + kstep;
;             PG8_LDB(B0, 0, 0); PG8_LDB(B1, 0, 1); PG8_SCHED; PG8_LDA(At, 0, 0); PG8_STAGE(PG8_SA(1, 1), a1 + hstepA, voffA);
;             PG8_WAIT_V(8); PG8_WAIT_L(0); PG8_BAR; PG8_MMA(0, 0, At, B0); PG8_MMA(0, 1, At, B1); PG8_BAR; PG8_SCHED;
;             PG8_LDA(At, 0, 1); PG8_STAGE(PG8_SB(0, 0), b2, voffB); PG8_STAGE(PG8_SB(0, 1), b2 + hstepB, voffB); PG8_STAGE(PG8_SA(0, 0), a2, voffA);
;             PG8_WAIT_V(8); PG8_WAIT_L(0); PG8_BAR; PG8_MMA(1, 0, At, B0); PG8_MMA(1, 1, At, B1); PG8_BAR; PG8_SCHED;
.LBB0_261:
	s_add_u32 s60, s6, s16
	s_addc_u32 s61, s7, s17
	s_add_u32 s64, s60, 0x100
	s_addc_u32 s65, s61, 0
	s_and_b64 s[48:49], s[14:15], exec
	s_cselect_b32 s49, s7, s65
	s_cselect_b32 s48, s6, s64
	s_add_u32 s16, s8, s16
	s_addc_u32 s17, s9, s17
	s_add_u32 s16, s16, 0x100
	ds_read_b128 v[144:147], v138
	ds_read_b128 v[148:151], v138 offset:1024
	ds_read_b128 v[152:155], v138 offset:2048
	ds_read_b128 v[156:159], v138 offset:3072
	ds_read_b128 v[160:163], v139
	ds_read_b128 v[164:167], v139 offset:1024
	ds_read_b128 v[168:171], v139 offset:2048
	ds_read_b128 v[172:175], v139 offset:3072
	s_addc_u32 s17, s17, 0
	s_and_b64 s[14:15], s[14:15], exec
	s_cselect_b32 s67, s9, s17
	s_cselect_b32 s66, s8, s16
	s_add_u32 s70, s60, 0x10080
	s_addc_u32 s71, s61, 0
	s_add_u32 s68, s66, 0x40000
	s_addc_u32 s69, s67, 0
	s_add_u32 s16, s48, 0x10000
	s_addc_u32 s17, s49, 0
	s_add_u32 s14, s66, 0x40080
	s_addc_u32 s15, s67, 0
	s_mov_b32 m0, s42
	v_lshl_add_u64 v[218:219], s[70:71], 0, v[134:135]
	ds_read_b128 v[176:179], v140
	ds_read_b128 v[180:183], v140 offset:1024
	ds_read_b128 v[194:197], v140 offset:2048
	ds_read_b128 v[198:201], v140 offset:3072
	ds_read_b128 v[202:205], v140 offset:4096
	ds_read_b128 v[206:209], v140 offset:5120
	ds_read_b128 v[210:213], v140 offset:6144
	ds_read_b128 v[214:217], v140 offset:7168
	global_load_lds_dwordx4 v[218:219], off
	v_lshl_add_u64 v[218:219], s[70:71], 0, v[130:131]
	s_mov_b32 m0, s43
	s_nop 0
	global_load_lds_dwordx4 v[218:219], off
	s_waitcnt vmcnt(8)
	s_waitcnt lgkmcnt(0)
	s_barrier
	s_waitcnt lgkmcnt(0)
	v_mfma_f32_16x16x32_bf16 v[124:127], v[144:147], v[176:179], v[124:127]
	v_mfma_f32_16x16x32_bf16 v[124:127], v[148:151], v[180:183], v[124:127]
	v_mfma_f32_16x16x32_bf16 v[120:123], v[152:155], v[176:179], v[120:123]
	v_mfma_f32_16x16x32_bf16 v[120:123], v[156:159], v[180:183], v[120:123]
	v_mfma_f32_16x16x32_bf16 v[116:119], v[144:147], v[194:197], v[116:119]
	v_mfma_f32_16x16x32_bf16 v[116:119], v[148:151], v[198:201], v[116:119]
	v_mfma_f32_16x16x32_bf16 v[108:111], v[152:155], v[194:197], v[108:111]
	v_mfma_f32_16x16x32_bf16 v[108:111], v[156:159], v[198:201], v[108:111]
	v_mfma_f32_16x16x32_bf16 v[100:103], v[144:147], v[202:205], v[100:103]
	v_mfma_f32_16x16x32_bf16 v[100:103], v[148:151], v[206:209], v[100:103]
	v_mfma_f32_16x16x32_bf16 v[96:99], v[152:155], v[202:205], v[96:99]
	v_mfma_f32_16x16x32_bf16 v[96:99], v[156:159], v[206:209], v[96:99]
	v_mfma_f32_16x16x32_bf16 v[84:87], v[144:147], v[210:213], v[84:87]
	v_mfma_f32_16x16x32_bf16 v[84:87], v[148:151], v[214:217], v[84:87]
	v_mfma_f32_16x16x32_bf16 v[80:83], v[152:155], v[210:213], v[80:83]
	v_mfma_f32_16x16x32_bf16 v[80:83], v[156:159], v[214:217], v[80:83]
	v_mfma_f32_16x16x32_bf16 v[112:115], v[160:163], v[176:179], v[112:115]
	v_mfma_f32_16x16x32_bf16 v[112:115], v[164:167], v[180:183], v[112:115]
	v_mfma_f32_16x16x32_bf16 v[104:107], v[168:171], v[176:179], v[104:107]
	v_mfma_f32_16x16x32_bf16 v[104:107], v[172:175], v[180:183], v[104:107]
	v_mfma_f32_16x16x32_bf16 v[92:95], v[160:163], v[194:197], v[92:95]
	v_mfma_f32_16x16x32_bf16 v[92:95], v[164:167], v[198:201], v[92:95]
	v_mfma_f32_16x16x32_bf16 v[88:91], v[168:171], v[194:197], v[88:91]
	v_mfma_f32_16x16x32_bf16 v[88:91], v[172:175], v[198:201], v[88:91]
	v_mfma_f32_16x16x32_bf16 v[76:79], v[160:163], v[202:205], v[76:79]
	v_mfma_f32_16x16x32_bf16 v[76:79], v[164:167], v[206:209], v[76:79]
	v_mfma_f32_16x16x32_bf16 v[72:75], v[168:171], v[202:205], v[72:75]
	v_mfma_f32_16x16x32_bf16 v[72:75], v[172:175], v[206:209], v[72:75]
	v_mfma_f32_16x16x32_bf16 v[68:71], v[160:163], v[210:213], v[68:71]
	v_mfma_f32_16x16x32_bf16 v[68:71], v[164:167], v[214:217], v[68:71]
	v_mfma_f32_16x16x32_bf16 v[64:67], v[168:171], v[210:213], v[64:67]
	v_mfma_f32_16x16x32_bf16 v[64:67], v[172:175], v[214:217], v[64:67]
	s_barrier
	s_mov_b32 m0, s50
	v_lshl_add_u64 v[218:219], s[66:67], 0, v[132:133]
	ds_read_b128 v[176:179], v140 offset:16384
	ds_read_b128 v[180:183], v140 offset:17408
	ds_read_b128 v[194:197], v140 offset:18432
	ds_read_b128 v[198:201], v140 offset:19456
	ds_read_b128 v[202:205], v140 offset:20480
	ds_read_b128 v[206:209], v140 offset:21504
	ds_read_b128 v[210:213], v140 offset:22528
	ds_read_b128 v[214:217], v140 offset:23552
	global_load_lds_dwordx4 v[218:219], off
	v_lshl_add_u64 v[220:221], s[66:67], 0, v[128:129]
	s_mov_b32 m0, s51
	v_lshl_add_u64 v[222:223], s[68:69], 0, v[132:133]
	global_load_lds_dwordx4 v[220:221], off
	s_mov_b32 m0, s54
	v_lshl_add_u64 v[224:225], s[48:49], 0, v[130:131]
	global_load_lds_dwordx4 v[222:223], off
	v_lshl_add_u64 v[222:223], s[68:69], 0, v[128:129]
	s_mov_b32 m0, s55
	s_nop 0
	global_load_lds_dwordx4 v[222:223], off
	v_lshl_add_u64 v[222:223], s[48:49], 0, v[134:135]
	s_mov_b32 m0, s20
	s_nop 0
	global_load_lds_dwordx4 v[222:223], off
	s_mov_b32 m0, s21
	s_nop 0
	global_load_lds_dwordx4 v[224:225], off
	s_waitcnt vmcnt(8)
	s_waitcnt lgkmcnt(0)
	s_barrier
; #define PG8_STAGE(bufoff, gbase, voff) do { _Pragma("unroll") for (int _i = 0; _i < 2; ++_i) \
;         __builtin_amdgcn_global_load_lds((const unsigned*)((const char*)(gbase) + (voff)[_i]), (LAS unsigned*)(lds + (bufoff) + ldsw + _i * 8192), 16, 0, 0); } while (0)
; #define PG8_LDA(dst, b, h) do { _Pragma("unroll") for (int m = 0; m < 4; ++m) _Pragma("unroll") for (int k = 0; k < 2; ++k) dst[m][k] = *(const LAS bf16x8*)(lds + PG8_SA(b, h) + aoff + m * 2048 + k * 1024); } while (0)
; #define PG8_LDB(dst, b, h) do { _Pragma("unroll") for (int n = 0; n < 2; ++n) _Pragma("unroll") for (int k = 0; k < 2; ++k) dst[n][k] = *(const LAS bf16x8*)(lds + PG8_SB(b, h) + boff + n * 2048 + k * 1024); } while (0)
; #define PG8_MMA(ai, bj, At, Bt) do { __builtin_amdgcn_s_setprio(1); _Pragma("unroll") for (int m = 0; m < 4; ++m) _Pragma("unroll") for (int n = 0; n < 2; ++n) _Pragma("unroll") for (int k = 0; k < 2; ++k) \
;         acc[ai][bj][m][n] = __builtin_amdgcn_mfma_f32_16x16x32_bf16(Bt[n][k], At[m][k], acc[ai][bj][m][n], 0, 0, 0); __builtin_amdgcn_s_setprio(0); } while (0)
; #define PG8_WAIT_V(n) asm volatile("s_waitcnt vmcnt(" #n ")" ::: "memory")
; #define PG8_WAIT_L(n) asm volatile("s_waitcnt lgkmcnt(" #n ")" ::: "memory")
; #define PG8_BAR __builtin_amdgcn_s_barrier()
; #define PG8_SCHED __builtin_amdgcn_sched_barrier(0)
; template <bool ALIGN_EPI, class Epi, class Sched>
; __device__ __forceinline__ void gemm_phase(LAS unsigned char* lds, const int lda, const int ldb, const int K, const Sched& S, const Epi& E, const size_t kstepA = (size_t)(BK * 2), const size_t kstepB = (size_t)(BK * 2)) {
;     ...
;             PG8_WAIT_V(8); PG8_WAIT_L(0); PG8_BAR; PG8_MMA(1, 0, At, B0); PG8_MMA(1, 1, At, B1); PG8_BAR; PG8_SCHED;
;             PG8_LDB(B0, 1, 0); PG8_LDB(B1, 1, 1); PG8_SCHED; PG8_LDA(At, 1, 0); PG8_STAGE(PG8_SA(0, 1), a2 + hstepA, voffA);
;             PG8_WAIT_V(8); PG8_WAIT_L(0); PG8_BAR; PG8_MMA(0, 0, At, B0); PG8_MMA(0, 1, At, B1); PG8_BAR; PG8_SCHED;
	s_waitcnt lgkmcnt(0)
	v_mfma_f32_16x16x32_bf16 v[60:63], v[144:147], v[176:179], v[60:63]
	v_mfma_f32_16x16x32_bf16 v[60:63], v[148:151], v[180:183], v[60:63]
	v_mfma_f32_16x16x32_bf16 v[56:59], v[152:155], v[176:179], v[56:59]
	v_mfma_f32_16x16x32_bf16 v[56:59], v[156:159], v[180:183], v[56:59]
	v_mfma_f32_16x16x32_bf16 v[52:55], v[144:147], v[194:197], v[52:55]
	v_mfma_f32_16x16x32_bf16 v[52:55], v[148:151], v[198:201], v[52:55]
	v_mfma_f32_16x16x32_bf16 v[48:51], v[152:155], v[194:197], v[48:51]
	v_mfma_f32_16x16x32_bf16 v[48:51], v[156:159], v[198:201], v[48:51]
	v_mfma_f32_16x16x32_bf16 v[36:39], v[144:147], v[202:205], v[36:39]
	v_mfma_f32_16x16x32_bf16 v[36:39], v[148:151], v[206:209], v[36:39]
	v_mfma_f32_16x16x32_bf16 v[32:35], v[152:155], v[202:205], v[32:35]
	v_mfma_f32_16x16x32_bf16 v[32:35], v[156:159], v[206:209], v[32:35]
	v_mfma_f32_16x16x32_bf16 v[20:23], v[144:147], v[210:213], v[20:23]
	v_mfma_f32_16x16x32_bf16 v[20:23], v[148:151], v[214:217], v[20:23]
	v_mfma_f32_16x16x32_bf16 v[16:19], v[152:155], v[210:213], v[16:19]
	v_mfma_f32_16x16x32_bf16 v[16:19], v[156:159], v[214:217], v[16:19]
	v_mfma_f32_16x16x32_bf16 v[44:47], v[160:163], v[176:179], v[44:47]
	v_mfma_f32_16x16x32_bf16 v[44:47], v[164:167], v[180:183], v[44:47]
	v_mfma_f32_16x16x32_bf16 v[40:43], v[168:171], v[176:179], v[40:43]
	v_mfma_f32_16x16x32_bf16 v[40:43], v[172:175], v[180:183], v[40:43]
	v_mfma_f32_16x16x32_bf16 v[28:31], v[160:163], v[194:197], v[28:31]
	v_mfma_f32_16x16x32_bf16 v[28:31], v[164:167], v[198:201], v[28:31]
	v_mfma_f32_16x16x32_bf16 v[24:27], v[168:171], v[194:197], v[24:27]
	v_mfma_f32_16x16x32_bf16 v[24:27], v[172:175], v[198:201], v[24:27]
	v_mfma_f32_16x16x32_bf16 v[12:15], v[160:163], v[202:205], v[12:15]
	v_mfma_f32_16x16x32_bf16 v[12:15], v[164:167], v[206:209], v[12:15]
	v_mfma_f32_16x16x32_bf16 v[8:11], v[168:171], v[202:205], v[8:11]
	v_mfma_f32_16x16x32_bf16 v[8:11], v[172:175], v[206:209], v[8:11]
	v_mfma_f32_16x16x32_bf16 v[4:7], v[160:163], v[210:213], v[4:7]
	v_mfma_f32_16x16x32_bf16 v[4:7], v[164:167], v[214:217], v[4:7]
	v_mfma_f32_16x16x32_bf16 v[0:3], v[168:171], v[210:213], v[0:3]
	v_mfma_f32_16x16x32_bf16 v[0:3], v[172:175], v[214:217], v[0:3]
	s_barrier
	ds_read_b128 v[144:147], v141
	ds_read_b128 v[148:151], v141 offset:1024
	ds_read_b128 v[152:155], v141 offset:2048
	ds_read_b128 v[156:159], v141 offset:3072
	ds_read_b128 v[160:163], v142
	ds_read_b128 v[164:167], v142 offset:1024
	ds_read_b128 v[168:171], v142 offset:2048
	ds_read_b128 v[172:175], v142 offset:3072
	s_mov_b32 m0, s22
	v_lshl_add_u64 v[226:227], s[16:17], 0, v[134:135]
	ds_read_b128 v[176:179], v140 offset:32768
	ds_read_b128 v[180:183], v140 offset:33792
	ds_read_b128 v[194:197], v140 offset:34816
	ds_read_b128 v[198:201], v140 offset:35840
	ds_read_b128 v[202:205], v140 offset:36864
	ds_read_b128 v[206:209], v140 offset:37888
	ds_read_b128 v[210:213], v140 offset:38912
	ds_read_b128 v[214:217], v140 offset:39936
	global_load_lds_dwordx4 v[226:227], off
	v_lshl_add_u64 v[226:227], s[16:17], 0, v[130:131]
	s_mov_b32 m0, s29
	s_nop 0
	global_load_lds_dwordx4 v[226:227], off
	s_waitcnt vmcnt(8)
	s_waitcnt lgkmcnt(0)
	s_barrier
	s_waitcnt lgkmcnt(0)
	v_mfma_f32_16x16x32_bf16 v[124:127], v[144:147], v[176:179], v[124:127]
	v_mfma_f32_16x16x32_bf16 v[124:127], v[148:151], v[180:183], v[124:127]
	v_mfma_f32_16x16x32_bf16 v[120:123], v[152:155], v[176:179], v[120:123]
	v_mfma_f32_16x16x32_bf16 v[120:123], v[156:159], v[180:183], v[120:123]
	v_mfma_f32_16x16x32_bf16 v[116:119], v[144:147], v[194:197], v[116:119]
	v_mfma_f32_16x16x32_bf16 v[116:119], v[148:151], v[198:201], v[116:119]
	v_mfma_f32_16x16x32_bf16 v[108:111], v[152:155], v[194:197], v[108:111]
	v_mfma_f32_16x16x32_bf16 v[108:111], v[156:159], v[198:201], v[108:111]
	v_mfma_f32_16x16x32_bf16 v[100:103], v[144:147], v[202:205], v[100:103]
	v_mfma_f32_16x16x32_bf16 v[100:103], v[148:151], v[206:209], v[100:103]
	v_mfma_f32_16x16x32_bf16 v[96:99], v[152:155], v[202:205], v[96:99]
	v_mfma_f32_16x16x32_bf16 v[96:99], v[156:159], v[206:209], v[96:99]
	v_mfma_f32_16x16x32_bf16 v[84:87], v[144:147], v[210:213], v[84:87]
	v_mfma_f32_16x16x32_bf16 v[84:87], v[148:151], v[214:217], v[84:87]
	v_mfma_f32_16x16x32_bf16 v[80:83], v[152:155], v[210:213], v[80:83]
	v_mfma_f32_16x16x32_bf16 v[80:83], v[156:159], v[214:217], v[80:83]
	v_mfma_f32_16x16x32_bf16 v[112:115], v[160:163], v[176:179], v[112:115]
	v_mfma_f32_16x16x32_bf16 v[112:115], v[164:167], v[180:183], v[112:115]
	v_mfma_f32_16x16x32_bf16 v[104:107], v[168:171], v[176:179], v[104:107]
	v_mfma_f32_16x16x32_bf16 v[104:107], v[172:175], v[180:183], v[104:107]
	v_mfma_f32_16x16x32_bf16 v[92:95], v[160:163], v[194:197], v[92:95]
	v_mfma_f32_16x16x32_bf16 v[92:95], v[164:167], v[198:201], v[92:95]
	v_mfma_f32_16x16x32_bf16 v[88:91], v[168:171], v[194:197], v[88:91]
	v_mfma_f32_16x16x32_bf16 v[88:91], v[172:175], v[198:201], v[88:91]
	v_mfma_f32_16x16x32_bf16 v[76:79], v[160:163], v[202:205], v[76:79]
	v_mfma_f32_16x16x32_bf16 v[76:79], v[164:167], v[206:209], v[76:79]
	v_mfma_f32_16x16x32_bf16 v[72:75], v[168:171], v[202:205], v[72:75]
	v_mfma_f32_16x16x32_bf16 v[72:75], v[172:175], v[206:209], v[72:75]
	v_mfma_f32_16x16x32_bf16 v[68:71], v[160:163], v[210:213], v[68:71]
	v_mfma_f32_16x16x32_bf16 v[68:71], v[164:167], v[214:217], v[68:71]
	v_mfma_f32_16x16x32_bf16 v[64:67], v[168:171], v[210:213], v[64:67]
	v_mfma_f32_16x16x32_bf16 v[64:67], v[172:175], v[214:217], v[64:67]
	s_barrier
; #define PG8_STAGE(bufoff, gbase, voff) do { _Pragma("unroll") for (int _i = 0; _i < 2; ++_i) \
;         __builtin_amdgcn_global_load_lds((const unsigned*)((const char*)(gbase) + (voff)[_i]), (LAS unsigned*)(lds + (bufoff) + ldsw + _i * 8192), 16, 0, 0); } while (0)
; #define PG8_LDA(dst, b, h) do { _Pragma("unroll") for (int m = 0; m < 4; ++m) _Pragma("unroll") for (int k = 0; k < 2; ++k) dst[m][k] = *(const LAS bf16x8*)(lds + PG8_SA(b, h) + aoff + m * 2048 + k * 1024); } while (0)
; #define PG8_MMA(ai, bj, At, Bt) do { __builtin_amdgcn_s_setprio(1); _Pragma("unroll") for (int m = 0; m < 4; ++m) _Pragma("unroll") for (int n = 0; n < 2; ++n) _Pragma("unroll") for (int k = 0; k < 2; ++k) \
;         acc[ai][bj][m][n] = __builtin_amdgcn_mfma_f32_16x16x32_bf16(Bt[n][k], At[m][k], acc[ai][bj][m][n], 0, 0, 0); __builtin_amdgcn_s_setprio(0); } while (0)
; #define PG8_WAIT_V(n) asm volatile("s_waitcnt vmcnt(" #n ")" ::: "memory")
; #define PG8_WAIT_L(n) asm volatile("s_waitcnt lgkmcnt(" #n ")" ::: "memory")
; #define PG8_BAR __builtin_amdgcn_s_barrier()
; #define PG8_SCHED __builtin_amdgcn_sched_barrier(0)
; template <bool ALIGN_EPI, class Epi, class Sched>
; __device__ __forceinline__ void gemm_phase(LAS unsigned char* lds, const int lda, const int ldb, const int K, const Sched& S, const Epi& E, const size_t kstepA = (size_t)(BK * 2), const size_t kstepB = (size_t)(BK * 2)) {
;     ...
;             PG8_LDA(At, 1, 1); PG8_STAGE(PG8_SB(1, 0), b3, voffB); PG8_STAGE(PG8_SB(1, 1), b3 + hstepB, voffB); PG8_STAGE(PG8_SA(1, 0), a3, voffA);
;             PG8_WAIT_V(8); PG8_WAIT_L(0); PG8_BAR; PG8_MMA(1, 0, At, B0); PG8_MMA(1, 1, At, B1); PG8_BAR; PG8_SCHED;
;         }
;         if constexpr (ALIGN_EPI) { if (wr == 0) PG8_BAR; }
	s_mov_b32 m0, s56
	v_lshl_add_u64 v[218:219], v[218:219], 0, s[10:11]
	ds_read_b128 v[176:179], v140 offset:49152
	ds_read_b128 v[180:183], v140 offset:50176
	ds_read_b128 v[194:197], v140 offset:51200
	ds_read_b128 v[198:201], v140 offset:52224
	ds_read_b128 v[202:205], v140 offset:53248
	ds_read_b128 v[206:209], v140 offset:54272
	ds_read_b128 v[210:213], v140 offset:55296
	ds_read_b128 v[214:217], v140 offset:56320
	global_load_lds_dwordx4 v[218:219], off
	v_lshl_add_u64 v[218:219], v[220:221], 0, s[10:11]
	s_mov_b32 m0, s57
	s_nop 0
	global_load_lds_dwordx4 v[218:219], off
	v_lshl_add_u64 v[218:219], s[14:15], 0, v[132:133]
	s_mov_b32 m0, s58
	s_nop 0
	global_load_lds_dwordx4 v[218:219], off
	v_lshl_add_u64 v[218:219], s[14:15], 0, v[128:129]
	s_mov_b32 m0, s59
	s_nop 0
	global_load_lds_dwordx4 v[218:219], off
	v_lshl_add_u64 v[218:219], v[222:223], 0, s[10:11]
	s_mov_b32 m0, s31
	s_nop 0
	global_load_lds_dwordx4 v[218:219], off
	v_lshl_add_u64 v[218:219], v[224:225], 0, s[10:11]
	s_mov_b32 m0, s33
	s_nop 0
	global_load_lds_dwordx4 v[218:219], off
	s_waitcnt vmcnt(8)
	s_waitcnt lgkmcnt(0)
	s_barrier
	s_waitcnt lgkmcnt(0)
	v_mfma_f32_16x16x32_bf16 v[60:63], v[144:147], v[176:179], v[60:63]
	v_mfma_f32_16x16x32_bf16 v[60:63], v[148:151], v[180:183], v[60:63]
	v_mfma_f32_16x16x32_bf16 v[56:59], v[152:155], v[176:179], v[56:59]
	v_mfma_f32_16x16x32_bf16 v[56:59], v[156:159], v[180:183], v[56:59]
	v_mfma_f32_16x16x32_bf16 v[52:55], v[144:147], v[194:197], v[52:55]
	v_mfma_f32_16x16x32_bf16 v[52:55], v[148:151], v[198:201], v[52:55]
	v_mfma_f32_16x16x32_bf16 v[48:51], v[152:155], v[194:197], v[48:51]
	v_mfma_f32_16x16x32_bf16 v[48:51], v[156:159], v[198:201], v[48:51]
	v_mfma_f32_16x16x32_bf16 v[36:39], v[144:147], v[202:205], v[36:39]
	v_mfma_f32_16x16x32_bf16 v[36:39], v[148:151], v[206:209], v[36:39]
	v_mfma_f32_16x16x32_bf16 v[32:35], v[152:155], v[202:205], v[32:35]
	v_mfma_f32_16x16x32_bf16 v[32:35], v[156:159], v[206:209], v[32:35]
	v_mfma_f32_16x16x32_bf16 v[20:23], v[144:147], v[210:213], v[20:23]
	v_mfma_f32_16x16x32_bf16 v[20:23], v[148:151], v[214:217], v[20:23]
	v_mfma_f32_16x16x32_bf16 v[16:19], v[152:155], v[210:213], v[16:19]
	v_mfma_f32_16x16x32_bf16 v[16:19], v[156:159], v[214:217], v[16:19]
	v_mfma_f32_16x16x32_bf16 v[44:47], v[160:163], v[176:179], v[44:47]
	v_mfma_f32_16x16x32_bf16 v[44:47], v[164:167], v[180:183], v[44:47]
	v_mfma_f32_16x16x32_bf16 v[40:43], v[168:171], v[176:179], v[40:43]
	v_mfma_f32_16x16x32_bf16 v[40:43], v[172:175], v[180:183], v[40:43]
	v_mfma_f32_16x16x32_bf16 v[28:31], v[160:163], v[194:197], v[28:31]
	v_mfma_f32_16x16x32_bf16 v[28:31], v[164:167], v[198:201], v[28:31]
	v_mfma_f32_16x16x32_bf16 v[24:27], v[168:171], v[194:197], v[24:27]
	v_mfma_f32_16x16x32_bf16 v[24:27], v[172:175], v[198:201], v[24:27]
	v_mfma_f32_16x16x32_bf16 v[12:15], v[160:163], v[202:205], v[12:15]
	v_mfma_f32_16x16x32_bf16 v[12:15], v[164:167], v[206:209], v[12:15]
	v_mfma_f32_16x16x32_bf16 v[8:11], v[168:171], v[202:205], v[8:11]
	v_mfma_f32_16x16x32_bf16 v[8:11], v[172:175], v[206:209], v[8:11]
	v_mfma_f32_16x16x32_bf16 v[4:7], v[160:163], v[210:213], v[4:7]
	v_mfma_f32_16x16x32_bf16 v[4:7], v[164:167], v[214:217], v[4:7]
	v_mfma_f32_16x16x32_bf16 v[0:3], v[168:171], v[210:213], v[0:3]
	v_mfma_f32_16x16x32_bf16 v[0:3], v[172:175], v[214:217], v[0:3]
	s_barrier
	s_andn2_b64 vcc, exec, s[12:13]
	s_mov_b64 s[14:15], -1
	s_mov_b64 s[12:13], 0
	s_mov_b64 s[16:17], 0x100
	s_cbranch_vccz .LBB0_261
	s_cmpk_lt_u32 s18, 0x100
	s_cbranch_scc0 .LBB0_264
	s_barrier

; #define PG8_STAGE(bufoff, gbase, voff) do { _Pragma("unroll") for (int _i = 0; _i < 2; ++_i) \
;         __builtin_amdgcn_global_load_lds((const unsigned*)((const char*)(gbase) + (voff)[_i]), (LAS unsigned*)(lds + (bufoff) + ldsw + _i * 8192), 16, 0, 0); } while (0)
; #define PG8_LDA(dst, b, h) do { _Pragma("unroll") for (int m = 0; m < 4; ++m) _Pragma("unroll") for (int k = 0; k < 2; ++k) dst[m][k] = *(const LAS bf16x8*)(lds + PG8_SA(b, h) + aoff + m * 2048 + k * 1024); } while (0)
; #define PG8_LDB(dst, b, h) do { _Pragma("unroll") for (int n = 0; n < 2; ++n) _Pragma("unroll") for (int k = 0; k < 2; ++k) dst[n][k] = *(const LAS bf16x8*)(lds + PG8_SB(b, h) + boff + n * 2048 + k * 1024); } while (0)
; #define PG8_MMA(ai, bj, At, Bt) do { __builtin_amdgcn_s_setprio(1); _Pragma("unroll") for (int m = 0; m < 4; ++m) _Pragma("unroll") for (int n = 0; n < 2; ++n) _Pragma("unroll") for (int k = 0; k < 2; ++k) \
;         acc[ai][bj][m][n] = __builtin_amdgcn_mfma_f32_16x16x32_bf16(Bt[n][k], At[m][k], acc[ai][bj][m][n], 0, 0, 0); __builtin_amdgcn_s_setprio(0); } while (0)
; #define PG8_WAIT_V(n) asm volatile("s_waitcnt vmcnt(" #n ")" ::: "memory")
; #define PG8_WAIT_L(n) asm volatile("s_waitcnt lgkmcnt(" #n ")" ::: "memory")
; #define PG8_BAR __builtin_amdgcn_s_barrier()
; #define PG8_SCHED __builtin_amdgcn_sched_barrier(0)
; template <bool ALIGN_EPI, class Epi, class Sched>
; __device__ __forceinline__ void gemm_phase(LAS unsigned char* lds, const int lda, const int ldb, const int K, const Sched& S, const Epi& E, const size_t kstepA = (size_t)(BK * 2), const size_t kstepB = (size_t)(BK * 2)) {
;     ...
;             const char* a1 = cA + (size_t)(t + 1) * kstepA;
;             const char* a2 = last ? nA : cA + (size_t)(t + 2) * kstepA; const char* b2 = last ? nB : cB + (size_t)(t + 2) * kstep;
;             const char* a3 = a2 + kstepA; const char* b3 = b2 + kstep;
;             PG8_LDB(B0, 0, 0); PG8_LDB(B1, 0, 1); PG8_SCHED; PG8_LDA(At, 0, 0); PG8_STAGE(PG8_SA(1, 1), a1 + hstepA, voffA);
;             PG8_WAIT_V(8); PG8_WAIT_L(0); PG8_BAR; PG8_MMA(0, 0, At, B0); PG8_MMA(0, 1, At, B1); PG8_BAR; PG8_SCHED;
;             PG8_LDA(At, 0, 1); PG8_STAGE(PG8_SB(0, 0), b2, voffB); PG8_STAGE(PG8_SB(0, 1), b2 + hstepB, voffB); PG8_STAGE(PG8_SA(0, 0), a2, voffA);
;             PG8_WAIT_V(8); PG8_WAIT_L(0); PG8_BAR; PG8_MMA(1, 0, At, B0); PG8_MMA(1, 1, At, B1); PG8_BAR; PG8_SCHED;
.LBB0_523:
	ds_read_b128 v[152:155], v141
	ds_read_b128 v[156:159], v141 offset:1024
	ds_read_b128 v[160:163], v141 offset:2048
	ds_read_b128 v[164:167], v141 offset:3072
	ds_read_b128 v[168:171], v147
	ds_read_b128 v[172:175], v147 offset:1024
	ds_read_b128 v[176:179], v147 offset:2048
	ds_read_b128 v[180:183], v147 offset:3072
	s_add_u32 s14, s10, s12
	s_addc_u32 s15, s11, s13
	s_add_u32 s14, s14, 0x984100
	s_addc_u32 s15, s15, 0
	s_add_u32 s61, s46, s12
	s_addc_u32 s62, s47, s13
	s_cmpk_eq_i32 s12, 0xf00
	s_cselect_b32 s17, s1, s15
	s_cselect_b32 s16, s0, s14
	s_cselect_b32 s15, s7, s62
	s_cselect_b32 s14, s6, s61
	s_mov_b32 m0, s51
	v_lshl_add_u64 v[222:223], v[142:143], 0, s[12:13]
	ds_read_b128 v[190:193], v148
	ds_read_b128 v[194:197], v148 offset:1024
	ds_read_b128 v[198:201], v148 offset:2048
	ds_read_b128 v[202:205], v148 offset:3072
	ds_read_b128 v[206:209], v148 offset:4096
	ds_read_b128 v[210:213], v148 offset:5120
	ds_read_b128 v[214:217], v148 offset:6144
	ds_read_b128 v[218:221], v148 offset:7168
	global_load_lds_dwordx4 v[222:223], off
	v_lshl_add_u64 v[222:223], v[144:145], 0, s[12:13]
	s_mov_b32 m0, s52
	s_nop 0
	global_load_lds_dwordx4 v[222:223], off
	s_waitcnt vmcnt(8)
	s_waitcnt lgkmcnt(0)
	s_barrier
	s_waitcnt lgkmcnt(0)
	v_mfma_f32_16x16x32_bf16 v[124:127], v[152:155], v[190:193], v[124:127]
	v_mfma_f32_16x16x32_bf16 v[124:127], v[156:159], v[194:197], v[124:127]
	v_mfma_f32_16x16x32_bf16 v[120:123], v[160:163], v[190:193], v[120:123]
	v_mfma_f32_16x16x32_bf16 v[120:123], v[164:167], v[194:197], v[120:123]
	v_mfma_f32_16x16x32_bf16 v[116:119], v[152:155], v[198:201], v[116:119]
	v_mfma_f32_16x16x32_bf16 v[116:119], v[156:159], v[202:205], v[116:119]
	v_mfma_f32_16x16x32_bf16 v[112:115], v[160:163], v[198:201], v[112:115]
	v_mfma_f32_16x16x32_bf16 v[112:115], v[164:167], v[202:205], v[112:115]
	v_mfma_f32_16x16x32_bf16 v[100:103], v[152:155], v[206:209], v[100:103]
	v_mfma_f32_16x16x32_bf16 v[100:103], v[156:159], v[210:213], v[100:103]
	v_mfma_f32_16x16x32_bf16 v[96:99], v[160:163], v[206:209], v[96:99]
	v_mfma_f32_16x16x32_bf16 v[96:99], v[164:167], v[210:213], v[96:99]
	v_mfma_f32_16x16x32_bf16 v[84:87], v[152:155], v[214:217], v[84:87]
	v_mfma_f32_16x16x32_bf16 v[84:87], v[156:159], v[218:221], v[84:87]
	v_mfma_f32_16x16x32_bf16 v[80:83], v[160:163], v[214:217], v[80:83]
	v_mfma_f32_16x16x32_bf16 v[80:83], v[164:167], v[218:221], v[80:83]
	v_mfma_f32_16x16x32_bf16 v[108:111], v[168:171], v[190:193], v[108:111]
	v_mfma_f32_16x16x32_bf16 v[108:111], v[172:175], v[194:197], v[108:111]
	v_mfma_f32_16x16x32_bf16 v[104:107], v[176:179], v[190:193], v[104:107]
	v_mfma_f32_16x16x32_bf16 v[104:107], v[180:183], v[194:197], v[104:107]
	v_mfma_f32_16x16x32_bf16 v[92:95], v[168:171], v[198:201], v[92:95]
	v_mfma_f32_16x16x32_bf16 v[92:95], v[172:175], v[202:205], v[92:95]
	v_mfma_f32_16x16x32_bf16 v[88:91], v[176:179], v[198:201], v[88:91]
	v_mfma_f32_16x16x32_bf16 v[88:91], v[180:183], v[202:205], v[88:91]
	v_mfma_f32_16x16x32_bf16 v[76:79], v[168:171], v[206:209], v[76:79]
	v_mfma_f32_16x16x32_bf16 v[76:79], v[172:175], v[210:213], v[76:79]
	v_mfma_f32_16x16x32_bf16 v[72:75], v[176:179], v[206:209], v[72:75]
	v_mfma_f32_16x16x32_bf16 v[72:75], v[180:183], v[210:213], v[72:75]
	v_mfma_f32_16x16x32_bf16 v[68:71], v[168:171], v[214:217], v[68:71]
	v_mfma_f32_16x16x32_bf16 v[68:71], v[172:175], v[218:221], v[68:71]
	v_mfma_f32_16x16x32_bf16 v[64:67], v[176:179], v[214:217], v[64:67]
	v_mfma_f32_16x16x32_bf16 v[64:67], v[180:183], v[218:221], v[64:67]
	s_barrier
	s_mov_b32 m0, s53
	v_lshl_add_u64 v[222:223], s[14:15], 0, v[136:137]
	s_add_u32 s62, s14, 0x80000
	ds_read_b128 v[190:193], v148 offset:16384
	ds_read_b128 v[194:197], v148 offset:17408
	ds_read_b128 v[198:201], v148 offset:18432
	ds_read_b128 v[202:205], v148 offset:19456
	ds_read_b128 v[206:209], v148 offset:20480
	ds_read_b128 v[210:213], v148 offset:21504
	ds_read_b128 v[214:217], v148 offset:22528
	ds_read_b128 v[218:221], v148 offset:23552
	global_load_lds_dwordx4 v[222:223], off
	v_lshl_add_u64 v[224:225], s[14:15], 0, v[132:133]
	s_mov_b32 m0, s54
	s_addc_u32 s63, s15, 0
	global_load_lds_dwordx4 v[224:225], off
	v_lshl_add_u64 v[226:227], s[62:63], 0, v[136:137]
	s_mov_b32 m0, s55
	v_lshl_add_u64 v[228:229], s[16:17], 0, v[134:135]
	global_load_lds_dwordx4 v[226:227], off
	v_lshl_add_u64 v[226:227], s[62:63], 0, v[132:133]
	s_mov_b32 m0, s56
	s_nop 0
	global_load_lds_dwordx4 v[226:227], off
	v_lshl_add_u64 v[226:227], s[16:17], 0, v[138:139]
	s_mov_b32 m0, s22
	s_nop 0
	global_load_lds_dwordx4 v[226:227], off
	s_mov_b32 m0, s30
	s_nop 0
	global_load_lds_dwordx4 v[228:229], off
	s_waitcnt vmcnt(8)
	s_waitcnt lgkmcnt(0)
	s_barrier
; #define PG8_STAGE(bufoff, gbase, voff) do { _Pragma("unroll") for (int _i = 0; _i < 2; ++_i) \
;         __builtin_amdgcn_global_load_lds((const unsigned*)((const char*)(gbase) + (voff)[_i]), (LAS unsigned*)(lds + (bufoff) + ldsw + _i * 8192), 16, 0, 0); } while (0)
; #define PG8_LDA(dst, b, h) do { _Pragma("unroll") for (int m = 0; m < 4; ++m) _Pragma("unroll") for (int k = 0; k < 2; ++k) dst[m][k] = *(const LAS bf16x8*)(lds + PG8_SA(b, h) + aoff + m * 2048 + k * 1024); } while (0)
; #define PG8_LDB(dst, b, h) do { _Pragma("unroll") for (int n = 0; n < 2; ++n) _Pragma("unroll") for (int k = 0; k < 2; ++k) dst[n][k] = *(const LAS bf16x8*)(lds + PG8_SB(b, h) + boff + n * 2048 + k * 1024); } while (0)
; #define PG8_MMA(ai, bj, At, Bt) do { __builtin_amdgcn_s_setprio(1); _Pragma("unroll") for (int m = 0; m < 4; ++m) _Pragma("unroll") for (int n = 0; n < 2; ++n) _Pragma("unroll") for (int k = 0; k < 2; ++k) \
;         acc[ai][bj][m][n] = __builtin_amdgcn_mfma_f32_16x16x32_bf16(Bt[n][k], At[m][k], acc[ai][bj][m][n], 0, 0, 0); __builtin_amdgcn_s_setprio(0); } while (0)
; #define PG8_WAIT_V(n) asm volatile("s_waitcnt vmcnt(" #n ")" ::: "memory")
; #define PG8_WAIT_L(n) asm volatile("s_waitcnt lgkmcnt(" #n ")" ::: "memory")
; #define PG8_BAR __builtin_amdgcn_s_barrier()
; #define PG8_SCHED __builtin_amdgcn_sched_barrier(0)
; template <bool ALIGN_EPI, class Epi, class Sched>
; __device__ __forceinline__ void gemm_phase(LAS unsigned char* lds, const int lda, const int ldb, const int K, const Sched& S, const Epi& E, const size_t kstepA = (size_t)(BK * 2), const size_t kstepB = (size_t)(BK * 2)) {
;     ...
;             PG8_WAIT_V(8); PG8_WAIT_L(0); PG8_BAR; PG8_MMA(1, 0, At, B0); PG8_MMA(1, 1, At, B1); PG8_BAR; PG8_SCHED;
;             PG8_LDB(B0, 1, 0); PG8_LDB(B1, 1, 1); PG8_SCHED; PG8_LDA(At, 1, 0); PG8_STAGE(PG8_SA(0, 1), a2 + hstepA, voffA);
;             PG8_WAIT_V(8); PG8_WAIT_L(0); PG8_BAR; PG8_MMA(0, 0, At, B0); PG8_MMA(0, 1, At, B1); PG8_BAR; PG8_SCHED;
	s_waitcnt lgkmcnt(0)
	v_mfma_f32_16x16x32_bf16 v[60:63], v[152:155], v[190:193], v[60:63]
	v_mfma_f32_16x16x32_bf16 v[60:63], v[156:159], v[194:197], v[60:63]
	v_mfma_f32_16x16x32_bf16 v[56:59], v[160:163], v[190:193], v[56:59]
	v_mfma_f32_16x16x32_bf16 v[56:59], v[164:167], v[194:197], v[56:59]
	v_mfma_f32_16x16x32_bf16 v[52:55], v[152:155], v[198:201], v[52:55]
	v_mfma_f32_16x16x32_bf16 v[52:55], v[156:159], v[202:205], v[52:55]
	v_mfma_f32_16x16x32_bf16 v[48:51], v[160:163], v[198:201], v[48:51]
	v_mfma_f32_16x16x32_bf16 v[48:51], v[164:167], v[202:205], v[48:51]
	v_mfma_f32_16x16x32_bf16 v[36:39], v[152:155], v[206:209], v[36:39]
	v_mfma_f32_16x16x32_bf16 v[36:39], v[156:159], v[210:213], v[36:39]
	v_mfma_f32_16x16x32_bf16 v[32:35], v[160:163], v[206:209], v[32:35]
	v_mfma_f32_16x16x32_bf16 v[32:35], v[164:167], v[210:213], v[32:35]
	v_mfma_f32_16x16x32_bf16 v[20:23], v[152:155], v[214:217], v[20:23]
	v_mfma_f32_16x16x32_bf16 v[20:23], v[156:159], v[218:221], v[20:23]
	v_mfma_f32_16x16x32_bf16 v[16:19], v[160:163], v[214:217], v[16:19]
	v_mfma_f32_16x16x32_bf16 v[16:19], v[164:167], v[218:221], v[16:19]
	v_mfma_f32_16x16x32_bf16 v[44:47], v[168:171], v[190:193], v[44:47]
	v_mfma_f32_16x16x32_bf16 v[44:47], v[172:175], v[194:197], v[44:47]
	v_mfma_f32_16x16x32_bf16 v[40:43], v[176:179], v[190:193], v[40:43]
	v_mfma_f32_16x16x32_bf16 v[40:43], v[180:183], v[194:197], v[40:43]
	v_mfma_f32_16x16x32_bf16 v[28:31], v[168:171], v[198:201], v[28:31]
	v_mfma_f32_16x16x32_bf16 v[28:31], v[172:175], v[202:205], v[28:31]
	v_mfma_f32_16x16x32_bf16 v[24:27], v[176:179], v[198:201], v[24:27]
	v_mfma_f32_16x16x32_bf16 v[24:27], v[180:183], v[202:205], v[24:27]
	v_mfma_f32_16x16x32_bf16 v[12:15], v[168:171], v[206:209], v[12:15]
	v_mfma_f32_16x16x32_bf16 v[12:15], v[172:175], v[210:213], v[12:15]
	v_mfma_f32_16x16x32_bf16 v[8:11], v[176:179], v[206:209], v[8:11]
	v_mfma_f32_16x16x32_bf16 v[8:11], v[180:183], v[210:213], v[8:11]
	v_mfma_f32_16x16x32_bf16 v[4:7], v[168:171], v[214:217], v[4:7]
	v_mfma_f32_16x16x32_bf16 v[4:7], v[172:175], v[218:221], v[4:7]
	v_mfma_f32_16x16x32_bf16 v[0:3], v[176:179], v[214:217], v[0:3]
	v_mfma_f32_16x16x32_bf16 v[0:3], v[180:183], v[218:221], v[0:3]
	s_barrier
	ds_read_b128 v[152:155], v149
	ds_read_b128 v[156:159], v149 offset:1024
	ds_read_b128 v[160:163], v149 offset:2048
	ds_read_b128 v[164:167], v149 offset:3072
	ds_read_b128 v[168:171], v150
	ds_read_b128 v[172:175], v150 offset:1024
	ds_read_b128 v[176:179], v150 offset:2048
	ds_read_b128 v[180:183], v150 offset:3072
	s_add_u32 s16, s16, 0x80000
	s_addc_u32 s17, s17, 0
	s_mov_b32 m0, s31
	v_lshl_add_u64 v[230:231], s[16:17], 0, v[138:139]
	ds_read_b128 v[190:193], v148 offset:32768
	ds_read_b128 v[194:197], v148 offset:33792
	ds_read_b128 v[198:201], v148 offset:34816
	ds_read_b128 v[202:205], v148 offset:35840
	ds_read_b128 v[206:209], v148 offset:36864
	ds_read_b128 v[210:213], v148 offset:37888
	ds_read_b128 v[214:217], v148 offset:38912
	ds_read_b128 v[218:221], v148 offset:39936
	global_load_lds_dwordx4 v[230:231], off
	v_lshl_add_u64 v[230:231], s[16:17], 0, v[134:135]
	s_mov_b32 m0, s33
	s_nop 0
	global_load_lds_dwordx4 v[230:231], off
	s_waitcnt vmcnt(8)
	s_waitcnt lgkmcnt(0)
	s_barrier
	s_waitcnt lgkmcnt(0)
	v_mfma_f32_16x16x32_bf16 v[124:127], v[152:155], v[190:193], v[124:127]
	v_mfma_f32_16x16x32_bf16 v[124:127], v[156:159], v[194:197], v[124:127]
	v_mfma_f32_16x16x32_bf16 v[120:123], v[160:163], v[190:193], v[120:123]
	v_mfma_f32_16x16x32_bf16 v[120:123], v[164:167], v[194:197], v[120:123]
	v_mfma_f32_16x16x32_bf16 v[116:119], v[152:155], v[198:201], v[116:119]
	v_mfma_f32_16x16x32_bf16 v[116:119], v[156:159], v[202:205], v[116:119]
	v_mfma_f32_16x16x32_bf16 v[112:115], v[160:163], v[198:201], v[112:115]
	v_mfma_f32_16x16x32_bf16 v[112:115], v[164:167], v[202:205], v[112:115]
	v_mfma_f32_16x16x32_bf16 v[100:103], v[152:155], v[206:209], v[100:103]
	v_mfma_f32_16x16x32_bf16 v[100:103], v[156:159], v[210:213], v[100:103]
	v_mfma_f32_16x16x32_bf16 v[96:99], v[160:163], v[206:209], v[96:99]
	v_mfma_f32_16x16x32_bf16 v[96:99], v[164:167], v[210:213], v[96:99]
	v_mfma_f32_16x16x32_bf16 v[84:87], v[152:155], v[214:217], v[84:87]
	v_mfma_f32_16x16x32_bf16 v[84:87], v[156:159], v[218:221], v[84:87]
	v_mfma_f32_16x16x32_bf16 v[80:83], v[160:163], v[214:217], v[80:83]
	v_mfma_f32_16x16x32_bf16 v[80:83], v[164:167], v[218:221], v[80:83]
	v_mfma_f32_16x16x32_bf16 v[108:111], v[168:171], v[190:193], v[108:111]
	v_mfma_f32_16x16x32_bf16 v[108:111], v[172:175], v[194:197], v[108:111]
	v_mfma_f32_16x16x32_bf16 v[104:107], v[176:179], v[190:193], v[104:107]
	v_mfma_f32_16x16x32_bf16 v[104:107], v[180:183], v[194:197], v[104:107]
	v_mfma_f32_16x16x32_bf16 v[92:95], v[168:171], v[198:201], v[92:95]
	v_mfma_f32_16x16x32_bf16 v[92:95], v[172:175], v[202:205], v[92:95]
	v_mfma_f32_16x16x32_bf16 v[88:91], v[176:179], v[198:201], v[88:91]
	v_mfma_f32_16x16x32_bf16 v[88:91], v[180:183], v[202:205], v[88:91]
	v_mfma_f32_16x16x32_bf16 v[76:79], v[168:171], v[206:209], v[76:79]
	v_mfma_f32_16x16x32_bf16 v[76:79], v[172:175], v[210:213], v[76:79]
	v_mfma_f32_16x16x32_bf16 v[72:75], v[176:179], v[206:209], v[72:75]
	v_mfma_f32_16x16x32_bf16 v[72:75], v[180:183], v[210:213], v[72:75]
	v_mfma_f32_16x16x32_bf16 v[68:71], v[168:171], v[214:217], v[68:71]
	v_mfma_f32_16x16x32_bf16 v[68:71], v[172:175], v[218:221], v[68:71]
	v_mfma_f32_16x16x32_bf16 v[64:67], v[176:179], v[214:217], v[64:67]
	v_mfma_f32_16x16x32_bf16 v[64:67], v[180:183], v[218:221], v[64:67]
	s_barrier
; #define PG8_STAGE(bufoff, gbase, voff) do { _Pragma("unroll") for (int _i = 0; _i < 2; ++_i) \
;         __builtin_amdgcn_global_load_lds((const unsigned*)((const char*)(gbase) + (voff)[_i]), (LAS unsigned*)(lds + (bufoff) + ldsw + _i * 8192), 16, 0, 0); } while (0)
; #define PG8_LDA(dst, b, h) do { _Pragma("unroll") for (int m = 0; m < 4; ++m) _Pragma("unroll") for (int k = 0; k < 2; ++k) dst[m][k] = *(const LAS bf16x8*)(lds + PG8_SA(b, h) + aoff + m * 2048 + k * 1024); } while (0)
; #define PG8_MMA(ai, bj, At, Bt) do { __builtin_amdgcn_s_setprio(1); _Pragma("unroll") for (int m = 0; m < 4; ++m) _Pragma("unroll") for (int n = 0; n < 2; ++n) _Pragma("unroll") for (int k = 0; k < 2; ++k) \
;         acc[ai][bj][m][n] = __builtin_amdgcn_mfma_f32_16x16x32_bf16(Bt[n][k], At[m][k], acc[ai][bj][m][n], 0, 0, 0); __builtin_amdgcn_s_setprio(0); } while (0)
; #define PG8_WAIT_V(n) asm volatile("s_waitcnt vmcnt(" #n ")" ::: "memory")
; #define PG8_WAIT_L(n) asm volatile("s_waitcnt lgkmcnt(" #n ")" ::: "memory")
; #define PG8_BAR __builtin_amdgcn_s_barrier()
; #define PG8_SCHED __builtin_amdgcn_sched_barrier(0)
; template <bool ALIGN_EPI, class Epi, class Sched>
; __device__ __forceinline__ void gemm_phase(LAS unsigned char* lds, const int lda, const int ldb, const int K, const Sched& S, const Epi& E, const size_t kstepA = (size_t)(BK * 2), const size_t kstepB = (size_t)(BK * 2)) {
;     ...
;             PG8_LDA(At, 1, 1); PG8_STAGE(PG8_SB(1, 0), b3, voffB); PG8_STAGE(PG8_SB(1, 1), b3 + hstepB, voffB); PG8_STAGE(PG8_SA(1, 0), a3, voffA);
;             PG8_WAIT_V(8); PG8_WAIT_L(0); PG8_BAR; PG8_MMA(1, 0, At, B0); PG8_MMA(1, 1, At, B1); PG8_BAR; PG8_SCHED;
;         }
;         if constexpr (ALIGN_EPI) { if (wr == 0) PG8_BAR; }
	s_mov_b32 m0, s57
	v_lshl_add_u64 v[222:223], v[222:223], 0, s[8:9]
	s_add_u32 s14, s14, 0x80080
	ds_read_b128 v[190:193], v148 offset:49152
	ds_read_b128 v[194:197], v148 offset:50176
	ds_read_b128 v[198:201], v148 offset:51200
	ds_read_b128 v[202:205], v148 offset:52224
	ds_read_b128 v[206:209], v148 offset:53248
	ds_read_b128 v[210:213], v148 offset:54272
	ds_read_b128 v[214:217], v148 offset:55296
	ds_read_b128 v[218:221], v148 offset:56320
	global_load_lds_dwordx4 v[222:223], off
	v_lshl_add_u64 v[222:223], v[224:225], 0, s[8:9]
	s_mov_b32 m0, s58
	s_addc_u32 s15, s15, 0
	global_load_lds_dwordx4 v[222:223], off
	v_lshl_add_u64 v[222:223], s[14:15], 0, v[136:137]
	s_mov_b32 m0, s59
	s_nop 0
	global_load_lds_dwordx4 v[222:223], off
	v_lshl_add_u64 v[222:223], s[14:15], 0, v[132:133]
	s_mov_b32 m0, s60
	s_nop 0
	global_load_lds_dwordx4 v[222:223], off
	v_lshl_add_u64 v[222:223], v[226:227], 0, s[8:9]
	s_mov_b32 m0, s42
	s_nop 0
	global_load_lds_dwordx4 v[222:223], off
	v_lshl_add_u64 v[222:223], v[228:229], 0, s[8:9]
	s_mov_b32 m0, s43
	s_nop 0
	global_load_lds_dwordx4 v[222:223], off
	s_waitcnt vmcnt(8)
	s_waitcnt lgkmcnt(0)
	s_barrier
	s_waitcnt lgkmcnt(0)
	v_mfma_f32_16x16x32_bf16 v[60:63], v[152:155], v[190:193], v[60:63]
	v_mfma_f32_16x16x32_bf16 v[60:63], v[156:159], v[194:197], v[60:63]
	v_mfma_f32_16x16x32_bf16 v[56:59], v[160:163], v[190:193], v[56:59]
	v_mfma_f32_16x16x32_bf16 v[56:59], v[164:167], v[194:197], v[56:59]
	v_mfma_f32_16x16x32_bf16 v[52:55], v[152:155], v[198:201], v[52:55]
	v_mfma_f32_16x16x32_bf16 v[52:55], v[156:159], v[202:205], v[52:55]
	v_mfma_f32_16x16x32_bf16 v[48:51], v[160:163], v[198:201], v[48:51]
	v_mfma_f32_16x16x32_bf16 v[48:51], v[164:167], v[202:205], v[48:51]
	v_mfma_f32_16x16x32_bf16 v[36:39], v[152:155], v[206:209], v[36:39]
	v_mfma_f32_16x16x32_bf16 v[36:39], v[156:159], v[210:213], v[36:39]
	v_mfma_f32_16x16x32_bf16 v[32:35], v[160:163], v[206:209], v[32:35]
	v_mfma_f32_16x16x32_bf16 v[32:35], v[164:167], v[210:213], v[32:35]
	v_mfma_f32_16x16x32_bf16 v[20:23], v[152:155], v[214:217], v[20:23]
	v_mfma_f32_16x16x32_bf16 v[20:23], v[156:159], v[218:221], v[20:23]
	v_mfma_f32_16x16x32_bf16 v[16:19], v[160:163], v[214:217], v[16:19]
	v_mfma_f32_16x16x32_bf16 v[16:19], v[164:167], v[218:221], v[16:19]
	v_mfma_f32_16x16x32_bf16 v[44:47], v[168:171], v[190:193], v[44:47]
	v_mfma_f32_16x16x32_bf16 v[44:47], v[172:175], v[194:197], v[44:47]
	v_mfma_f32_16x16x32_bf16 v[40:43], v[176:179], v[190:193], v[40:43]
	v_mfma_f32_16x16x32_bf16 v[40:43], v[180:183], v[194:197], v[40:43]
	v_mfma_f32_16x16x32_bf16 v[28:31], v[168:171], v[198:201], v[28:31]
	v_mfma_f32_16x16x32_bf16 v[28:31], v[172:175], v[202:205], v[28:31]
	v_mfma_f32_16x16x32_bf16 v[24:27], v[176:179], v[198:201], v[24:27]
	v_mfma_f32_16x16x32_bf16 v[24:27], v[180:183], v[202:205], v[24:27]
	v_mfma_f32_16x16x32_bf16 v[12:15], v[168:171], v[206:209], v[12:15]
	v_mfma_f32_16x16x32_bf16 v[12:15], v[172:175], v[210:213], v[12:15]
	v_mfma_f32_16x16x32_bf16 v[8:11], v[176:179], v[206:209], v[8:11]
	v_mfma_f32_16x16x32_bf16 v[8:11], v[180:183], v[210:213], v[8:11]
	v_mfma_f32_16x16x32_bf16 v[4:7], v[168:171], v[214:217], v[4:7]
	v_mfma_f32_16x16x32_bf16 v[4:7], v[172:175], v[218:221], v[4:7]
	v_mfma_f32_16x16x32_bf16 v[0:3], v[176:179], v[214:217], v[0:3]
	v_mfma_f32_16x16x32_bf16 v[0:3], v[180:183], v[218:221], v[0:3]
	s_barrier
	s_add_i32 s50, s50, 2
	s_add_u32 s12, s12, 0x100
	s_addc_u32 s13, s13, 0
	s_cmp_gt_u32 s50, 29
	s_cbranch_scc0 .LBB0_523
	s_cmpk_lt_u32 s21, 0x100
	s_cbranch_scc0 .LBB0_526
	s_barrier

; #define PG8_STAGE(bufoff, gbase, voff) do { _Pragma("unroll") for (int _i = 0; _i < 2; ++_i) \
;         __builtin_amdgcn_global_load_lds((const unsigned*)((const char*)(gbase) + (voff)[_i]), (LAS unsigned*)(lds + (bufoff) + ldsw + _i * 8192), 16, 0, 0); } while (0)
; #define PG8_LDA(dst, b, h) do { _Pragma("unroll") for (int m = 0; m < 4; ++m) _Pragma("unroll") for (int k = 0; k < 2; ++k) dst[m][k] = *(const LAS bf16x8*)(lds + PG8_SA(b, h) + aoff + m * 2048 + k * 1024); } while (0)
; #define PG8_LDB(dst, b, h) do { _Pragma("unroll") for (int n = 0; n < 2; ++n) _Pragma("unroll") for (int k = 0; k < 2; ++k) dst[n][k] = *(const LAS bf16x8*)(lds + PG8_SB(b, h) + boff + n * 2048 + k * 1024); } while (0)
; #define PG8_MMA(ai, bj, At, Bt) do { __builtin_amdgcn_s_setprio(1); _Pragma("unroll") for (int m = 0; m < 4; ++m) _Pragma("unroll") for (int n = 0; n < 2; ++n) _Pragma("unroll") for (int k = 0; k < 2; ++k) \
;         acc[ai][bj][m][n] = __builtin_amdgcn_mfma_f32_16x16x32_bf16(Bt[n][k], At[m][k], acc[ai][bj][m][n], 0, 0, 0); __builtin_amdgcn_s_setprio(0); } while (0)
; #define PG8_WAIT_V(n) asm volatile("s_waitcnt vmcnt(" #n ")" ::: "memory")
; #define PG8_WAIT_L(n) asm volatile("s_waitcnt lgkmcnt(" #n ")" ::: "memory")
; #define PG8_BAR __builtin_amdgcn_s_barrier()
; #define PG8_SCHED __builtin_amdgcn_sched_barrier(0)
; template <bool ALIGN_EPI, class Epi, class Sched>
; __device__ __forceinline__ void gemm_phase(LAS unsigned char* lds, const int lda, const int ldb, const int K, const Sched& S, const Epi& E, const size_t kstepA = (size_t)(BK * 2), const size_t kstepB = (size_t)(BK * 2)) {
;     ...
;             const char* a1 = cA + (size_t)(t + 1) * kstepA;
;             const char* a2 = last ? nA : cA + (size_t)(t + 2) * kstepA; const char* b2 = last ? nB : cB + (size_t)(t + 2) * kstep;
;             const char* a3 = a2 + kstepA; const char* b3 = b2 + kstep;
;             PG8_LDB(B0, 0, 0); PG8_LDB(B1, 0, 1); PG8_SCHED; PG8_LDA(At, 0, 0); PG8_STAGE(PG8_SA(1, 1), a1 + hstepA, voffA);
;             PG8_WAIT_V(8); PG8_WAIT_L(0); PG8_BAR; PG8_MMA(0, 0, At, B0); PG8_MMA(0, 1, At, B1); PG8_BAR; PG8_SCHED;
;             PG8_LDA(At, 0, 1); PG8_STAGE(PG8_SB(0, 0), b2, voffB); PG8_STAGE(PG8_SB(0, 1), b2 + hstepB, voffB); PG8_STAGE(PG8_SA(0, 0), a2, voffA);
;             PG8_WAIT_V(8); PG8_WAIT_L(0); PG8_BAR; PG8_MMA(1, 0, At, B0); PG8_MMA(1, 1, At, B1); PG8_BAR; PG8_SCHED;
.LBB0_586:
	ds_read_b128 v[152:155], v146
	ds_read_b128 v[156:159], v146 offset:1024
	ds_read_b128 v[160:163], v146 offset:2048
	ds_read_b128 v[164:167], v146 offset:3072
	ds_read_b128 v[168:171], v147
	ds_read_b128 v[172:175], v147 offset:1024
	ds_read_b128 v[176:179], v147 offset:2048
	ds_read_b128 v[180:183], v147 offset:3072
	s_add_u32 s14, s10, s12
	s_addc_u32 s15, s11, s13
	s_add_u32 s14, s14, 0xb84100
	s_addc_u32 s15, s15, 0
	s_add_u32 s60, s43, s12
	s_addc_u32 s61, s46, s13
	s_cmpk_eq_i32 s12, 0x300
	s_cselect_b32 s17, s1, s15
	s_cselect_b32 s16, s0, s14
	s_cselect_b32 s15, s7, s61
	s_cselect_b32 s14, s6, s60
	s_mov_b32 m0, s50
	v_lshl_add_u64 v[222:223], v[140:141], 0, s[12:13]
	ds_read_b128 v[190:193], v148
	ds_read_b128 v[194:197], v148 offset:1024
	ds_read_b128 v[198:201], v148 offset:2048
	ds_read_b128 v[202:205], v148 offset:3072
	ds_read_b128 v[206:209], v148 offset:4096
	ds_read_b128 v[210:213], v148 offset:5120
	ds_read_b128 v[214:217], v148 offset:6144
	ds_read_b128 v[218:221], v148 offset:7168
	global_load_lds_dwordx4 v[222:223], off
	v_lshl_add_u64 v[222:223], v[142:143], 0, s[12:13]
	s_mov_b32 m0, s51
	s_nop 0
	global_load_lds_dwordx4 v[222:223], off
	s_waitcnt vmcnt(8)
	s_waitcnt lgkmcnt(0)
	s_barrier
	s_waitcnt lgkmcnt(0)
	v_mfma_f32_16x16x32_bf16 v[124:127], v[152:155], v[190:193], v[124:127]
	v_mfma_f32_16x16x32_bf16 v[124:127], v[156:159], v[194:197], v[124:127]
	v_mfma_f32_16x16x32_bf16 v[120:123], v[160:163], v[190:193], v[120:123]
	v_mfma_f32_16x16x32_bf16 v[120:123], v[164:167], v[194:197], v[120:123]
	v_mfma_f32_16x16x32_bf16 v[116:119], v[152:155], v[198:201], v[116:119]
	v_mfma_f32_16x16x32_bf16 v[116:119], v[156:159], v[202:205], v[116:119]
	v_mfma_f32_16x16x32_bf16 v[108:111], v[160:163], v[198:201], v[108:111]
	v_mfma_f32_16x16x32_bf16 v[108:111], v[164:167], v[202:205], v[108:111]
	v_mfma_f32_16x16x32_bf16 v[100:103], v[152:155], v[206:209], v[100:103]
	v_mfma_f32_16x16x32_bf16 v[100:103], v[156:159], v[210:213], v[100:103]
	v_mfma_f32_16x16x32_bf16 v[96:99], v[160:163], v[206:209], v[96:99]
	v_mfma_f32_16x16x32_bf16 v[96:99], v[164:167], v[210:213], v[96:99]
	v_mfma_f32_16x16x32_bf16 v[84:87], v[152:155], v[214:217], v[84:87]
	v_mfma_f32_16x16x32_bf16 v[84:87], v[156:159], v[218:221], v[84:87]
	v_mfma_f32_16x16x32_bf16 v[80:83], v[160:163], v[214:217], v[80:83]
	v_mfma_f32_16x16x32_bf16 v[80:83], v[164:167], v[218:221], v[80:83]
	v_mfma_f32_16x16x32_bf16 v[112:115], v[168:171], v[190:193], v[112:115]
	v_mfma_f32_16x16x32_bf16 v[112:115], v[172:175], v[194:197], v[112:115]
	v_mfma_f32_16x16x32_bf16 v[104:107], v[176:179], v[190:193], v[104:107]
	v_mfma_f32_16x16x32_bf16 v[104:107], v[180:183], v[194:197], v[104:107]
	v_mfma_f32_16x16x32_bf16 v[92:95], v[168:171], v[198:201], v[92:95]
	v_mfma_f32_16x16x32_bf16 v[92:95], v[172:175], v[202:205], v[92:95]
	v_mfma_f32_16x16x32_bf16 v[88:91], v[176:179], v[198:201], v[88:91]
	v_mfma_f32_16x16x32_bf16 v[88:91], v[180:183], v[202:205], v[88:91]
	v_mfma_f32_16x16x32_bf16 v[76:79], v[168:171], v[206:209], v[76:79]
	v_mfma_f32_16x16x32_bf16 v[76:79], v[172:175], v[210:213], v[76:79]
	v_mfma_f32_16x16x32_bf16 v[72:75], v[176:179], v[206:209], v[72:75]
	v_mfma_f32_16x16x32_bf16 v[72:75], v[180:183], v[210:213], v[72:75]
	v_mfma_f32_16x16x32_bf16 v[68:71], v[168:171], v[214:217], v[68:71]
	v_mfma_f32_16x16x32_bf16 v[68:71], v[172:175], v[218:221], v[68:71]
	v_mfma_f32_16x16x32_bf16 v[64:67], v[176:179], v[214:217], v[64:67]
	v_mfma_f32_16x16x32_bf16 v[64:67], v[180:183], v[218:221], v[64:67]
	s_barrier
	s_mov_b32 m0, s52
	v_lshl_add_u64 v[222:223], s[14:15], 0, v[136:137]
	s_add_u32 s60, s14, 0x80000
	ds_read_b128 v[190:193], v148 offset:16384
	ds_read_b128 v[194:197], v148 offset:17408
	ds_read_b128 v[198:201], v148 offset:18432
	ds_read_b128 v[202:205], v148 offset:19456
	ds_read_b128 v[206:209], v148 offset:20480
	ds_read_b128 v[210:213], v148 offset:21504
	ds_read_b128 v[214:217], v148 offset:22528
	ds_read_b128 v[218:221], v148 offset:23552
	global_load_lds_dwordx4 v[222:223], off
	v_lshl_add_u64 v[224:225], s[14:15], 0, v[132:133]
	s_mov_b32 m0, s53
	s_addc_u32 s61, s15, 0
	global_load_lds_dwordx4 v[224:225], off
	v_lshl_add_u64 v[226:227], s[60:61], 0, v[136:137]
	s_mov_b32 m0, s54
	v_lshl_add_u64 v[228:229], s[16:17], 0, v[134:135]
	global_load_lds_dwordx4 v[226:227], off
	v_lshl_add_u64 v[226:227], s[60:61], 0, v[132:133]
	s_mov_b32 m0, s55
	s_nop 0
	global_load_lds_dwordx4 v[226:227], off
	v_lshl_add_u64 v[226:227], s[16:17], 0, v[138:139]
	s_mov_b32 m0, s21
	s_nop 0
	global_load_lds_dwordx4 v[226:227], off
	s_mov_b32 m0, s22
	s_nop 0
	global_load_lds_dwordx4 v[228:229], off
	s_waitcnt vmcnt(8)
	s_waitcnt lgkmcnt(0)
	s_barrier
; #define PG8_STAGE(bufoff, gbase, voff) do { _Pragma("unroll") for (int _i = 0; _i < 2; ++_i) \
;         __builtin_amdgcn_global_load_lds((const unsigned*)((const char*)(gbase) + (voff)[_i]), (LAS unsigned*)(lds + (bufoff) + ldsw + _i * 8192), 16, 0, 0); } while (0)
; #define PG8_LDA(dst, b, h) do { _Pragma("unroll") for (int m = 0; m < 4; ++m) _Pragma("unroll") for (int k = 0; k < 2; ++k) dst[m][k] = *(const LAS bf16x8*)(lds + PG8_SA(b, h) + aoff + m * 2048 + k * 1024); } while (0)
; #define PG8_LDB(dst, b, h) do { _Pragma("unroll") for (int n = 0; n < 2; ++n) _Pragma("unroll") for (int k = 0; k < 2; ++k) dst[n][k] = *(const LAS bf16x8*)(lds + PG8_SB(b, h) + boff + n * 2048 + k * 1024); } while (0)
; #define PG8_MMA(ai, bj, At, Bt) do { __builtin_amdgcn_s_setprio(1); _Pragma("unroll") for (int m = 0; m < 4; ++m) _Pragma("unroll") for (int n = 0; n < 2; ++n) _Pragma("unroll") for (int k = 0; k < 2; ++k) \
;         acc[ai][bj][m][n] = __builtin_amdgcn_mfma_f32_16x16x32_bf16(Bt[n][k], At[m][k], acc[ai][bj][m][n], 0, 0, 0); __builtin_amdgcn_s_setprio(0); } while (0)
; #define PG8_WAIT_V(n) asm volatile("s_waitcnt vmcnt(" #n ")" ::: "memory")
; #define PG8_WAIT_L(n) asm volatile("s_waitcnt lgkmcnt(" #n ")" ::: "memory")
; #define PG8_BAR __builtin_amdgcn_s_barrier()
; #define PG8_SCHED __builtin_amdgcn_sched_barrier(0)
; template <bool ALIGN_EPI, class Epi, class Sched>
; __device__ __forceinline__ void gemm_phase(LAS unsigned char* lds, const int lda, const int ldb, const int K, const Sched& S, const Epi& E, const size_t kstepA = (size_t)(BK * 2), const size_t kstepB = (size_t)(BK * 2)) {
;     ...
;             PG8_WAIT_V(8); PG8_WAIT_L(0); PG8_BAR; PG8_MMA(1, 0, At, B0); PG8_MMA(1, 1, At, B1); PG8_BAR; PG8_SCHED;
;             PG8_LDB(B0, 1, 0); PG8_LDB(B1, 1, 1); PG8_SCHED; PG8_LDA(At, 1, 0); PG8_STAGE(PG8_SA(0, 1), a2 + hstepA, voffA);
;             PG8_WAIT_V(8); PG8_WAIT_L(0); PG8_BAR; PG8_MMA(0, 0, At, B0); PG8_MMA(0, 1, At, B1); PG8_BAR; PG8_SCHED;
	s_waitcnt lgkmcnt(0)
	v_mfma_f32_16x16x32_bf16 v[60:63], v[152:155], v[190:193], v[60:63]
	v_mfma_f32_16x16x32_bf16 v[60:63], v[156:159], v[194:197], v[60:63]
	v_mfma_f32_16x16x32_bf16 v[56:59], v[160:163], v[190:193], v[56:59]
	v_mfma_f32_16x16x32_bf16 v[56:59], v[164:167], v[194:197], v[56:59]
	v_mfma_f32_16x16x32_bf16 v[52:55], v[152:155], v[198:201], v[52:55]
	v_mfma_f32_16x16x32_bf16 v[52:55], v[156:159], v[202:205], v[52:55]
	v_mfma_f32_16x16x32_bf16 v[48:51], v[160:163], v[198:201], v[48:51]
	v_mfma_f32_16x16x32_bf16 v[48:51], v[164:167], v[202:205], v[48:51]
	v_mfma_f32_16x16x32_bf16 v[36:39], v[152:155], v[206:209], v[36:39]
	v_mfma_f32_16x16x32_bf16 v[36:39], v[156:159], v[210:213], v[36:39]
	v_mfma_f32_16x16x32_bf16 v[32:35], v[160:163], v[206:209], v[32:35]
	v_mfma_f32_16x16x32_bf16 v[32:35], v[164:167], v[210:213], v[32:35]
	v_mfma_f32_16x16x32_bf16 v[20:23], v[152:155], v[214:217], v[20:23]
	v_mfma_f32_16x16x32_bf16 v[20:23], v[156:159], v[218:221], v[20:23]
	v_mfma_f32_16x16x32_bf16 v[16:19], v[160:163], v[214:217], v[16:19]
	v_mfma_f32_16x16x32_bf16 v[16:19], v[164:167], v[218:221], v[16:19]
	v_mfma_f32_16x16x32_bf16 v[44:47], v[168:171], v[190:193], v[44:47]
	v_mfma_f32_16x16x32_bf16 v[44:47], v[172:175], v[194:197], v[44:47]
	v_mfma_f32_16x16x32_bf16 v[40:43], v[176:179], v[190:193], v[40:43]
	v_mfma_f32_16x16x32_bf16 v[40:43], v[180:183], v[194:197], v[40:43]
	v_mfma_f32_16x16x32_bf16 v[28:31], v[168:171], v[198:201], v[28:31]
	v_mfma_f32_16x16x32_bf16 v[28:31], v[172:175], v[202:205], v[28:31]
	v_mfma_f32_16x16x32_bf16 v[24:27], v[176:179], v[198:201], v[24:27]
	v_mfma_f32_16x16x32_bf16 v[24:27], v[180:183], v[202:205], v[24:27]
	v_mfma_f32_16x16x32_bf16 v[12:15], v[168:171], v[206:209], v[12:15]
	v_mfma_f32_16x16x32_bf16 v[12:15], v[172:175], v[210:213], v[12:15]
	v_mfma_f32_16x16x32_bf16 v[8:11], v[176:179], v[206:209], v[8:11]
	v_mfma_f32_16x16x32_bf16 v[8:11], v[180:183], v[210:213], v[8:11]
	v_mfma_f32_16x16x32_bf16 v[4:7], v[168:171], v[214:217], v[4:7]
	v_mfma_f32_16x16x32_bf16 v[4:7], v[172:175], v[218:221], v[4:7]
	v_mfma_f32_16x16x32_bf16 v[0:3], v[176:179], v[214:217], v[0:3]
	v_mfma_f32_16x16x32_bf16 v[0:3], v[180:183], v[218:221], v[0:3]
	s_barrier
	ds_read_b128 v[152:155], v149
	ds_read_b128 v[156:159], v149 offset:1024
	ds_read_b128 v[160:163], v149 offset:2048
	ds_read_b128 v[164:167], v149 offset:3072
	ds_read_b128 v[168:171], v150
	ds_read_b128 v[172:175], v150 offset:1024
	ds_read_b128 v[176:179], v150 offset:2048
	ds_read_b128 v[180:183], v150 offset:3072
	s_add_u32 s16, s16, 0x20000
	s_addc_u32 s17, s17, 0
	s_mov_b32 m0, s29
	v_lshl_add_u64 v[230:231], s[16:17], 0, v[138:139]
	ds_read_b128 v[190:193], v148 offset:32768
	ds_read_b128 v[194:197], v148 offset:33792
	ds_read_b128 v[198:201], v148 offset:34816
	ds_read_b128 v[202:205], v148 offset:35840
	ds_read_b128 v[206:209], v148 offset:36864
	ds_read_b128 v[210:213], v148 offset:37888
	ds_read_b128 v[214:217], v148 offset:38912
	ds_read_b128 v[218:221], v148 offset:39936
	global_load_lds_dwordx4 v[230:231], off
	v_lshl_add_u64 v[230:231], s[16:17], 0, v[134:135]
	s_mov_b32 m0, s30
	s_nop 0
	global_load_lds_dwordx4 v[230:231], off
	s_waitcnt vmcnt(8)
	s_waitcnt lgkmcnt(0)
	s_barrier
	s_waitcnt lgkmcnt(0)
	v_mfma_f32_16x16x32_bf16 v[124:127], v[152:155], v[190:193], v[124:127]
	v_mfma_f32_16x16x32_bf16 v[124:127], v[156:159], v[194:197], v[124:127]
	v_mfma_f32_16x16x32_bf16 v[120:123], v[160:163], v[190:193], v[120:123]
	v_mfma_f32_16x16x32_bf16 v[120:123], v[164:167], v[194:197], v[120:123]
	v_mfma_f32_16x16x32_bf16 v[116:119], v[152:155], v[198:201], v[116:119]
	v_mfma_f32_16x16x32_bf16 v[116:119], v[156:159], v[202:205], v[116:119]
	v_mfma_f32_16x16x32_bf16 v[108:111], v[160:163], v[198:201], v[108:111]
	v_mfma_f32_16x16x32_bf16 v[108:111], v[164:167], v[202:205], v[108:111]
	v_mfma_f32_16x16x32_bf16 v[100:103], v[152:155], v[206:209], v[100:103]
	v_mfma_f32_16x16x32_bf16 v[100:103], v[156:159], v[210:213], v[100:103]
	v_mfma_f32_16x16x32_bf16 v[96:99], v[160:163], v[206:209], v[96:99]
	v_mfma_f32_16x16x32_bf16 v[96:99], v[164:167], v[210:213], v[96:99]
	v_mfma_f32_16x16x32_bf16 v[84:87], v[152:155], v[214:217], v[84:87]
	v_mfma_f32_16x16x32_bf16 v[84:87], v[156:159], v[218:221], v[84:87]
	v_mfma_f32_16x16x32_bf16 v[80:83], v[160:163], v[214:217], v[80:83]
	v_mfma_f32_16x16x32_bf16 v[80:83], v[164:167], v[218:221], v[80:83]
	v_mfma_f32_16x16x32_bf16 v[112:115], v[168:171], v[190:193], v[112:115]
	v_mfma_f32_16x16x32_bf16 v[112:115], v[172:175], v[194:197], v[112:115]
	v_mfma_f32_16x16x32_bf16 v[104:107], v[176:179], v[190:193], v[104:107]
	v_mfma_f32_16x16x32_bf16 v[104:107], v[180:183], v[194:197], v[104:107]
	v_mfma_f32_16x16x32_bf16 v[92:95], v[168:171], v[198:201], v[92:95]
	v_mfma_f32_16x16x32_bf16 v[92:95], v[172:175], v[202:205], v[92:95]
	v_mfma_f32_16x16x32_bf16 v[88:91], v[176:179], v[198:201], v[88:91]
	v_mfma_f32_16x16x32_bf16 v[88:91], v[180:183], v[202:205], v[88:91]
	v_mfma_f32_16x16x32_bf16 v[76:79], v[168:171], v[206:209], v[76:79]
	v_mfma_f32_16x16x32_bf16 v[76:79], v[172:175], v[210:213], v[76:79]
	v_mfma_f32_16x16x32_bf16 v[72:75], v[176:179], v[206:209], v[72:75]
	v_mfma_f32_16x16x32_bf16 v[72:75], v[180:183], v[210:213], v[72:75]
	v_mfma_f32_16x16x32_bf16 v[68:71], v[168:171], v[214:217], v[68:71]
	v_mfma_f32_16x16x32_bf16 v[68:71], v[172:175], v[218:221], v[68:71]
	v_mfma_f32_16x16x32_bf16 v[64:67], v[176:179], v[214:217], v[64:67]
	v_mfma_f32_16x16x32_bf16 v[64:67], v[180:183], v[218:221], v[64:67]
	s_barrier
; #define PG8_STAGE(bufoff, gbase, voff) do { _Pragma("unroll") for (int _i = 0; _i < 2; ++_i) \
;         __builtin_amdgcn_global_load_lds((const unsigned*)((const char*)(gbase) + (voff)[_i]), (LAS unsigned*)(lds + (bufoff) + ldsw + _i * 8192), 16, 0, 0); } while (0)
; #define PG8_LDA(dst, b, h) do { _Pragma("unroll") for (int m = 0; m < 4; ++m) _Pragma("unroll") for (int k = 0; k < 2; ++k) dst[m][k] = *(const LAS bf16x8*)(lds + PG8_SA(b, h) + aoff + m * 2048 + k * 1024); } while (0)
; #define PG8_MMA(ai, bj, At, Bt) do { __builtin_amdgcn_s_setprio(1); _Pragma("unroll") for (int m = 0; m < 4; ++m) _Pragma("unroll") for (int n = 0; n < 2; ++n) _Pragma("unroll") for (int k = 0; k < 2; ++k) \
;         acc[ai][bj][m][n] = __builtin_amdgcn_mfma_f32_16x16x32_bf16(Bt[n][k], At[m][k], acc[ai][bj][m][n], 0, 0, 0); __builtin_amdgcn_s_setprio(0); } while (0)
; #define PG8_WAIT_V(n) asm volatile("s_waitcnt vmcnt(" #n ")" ::: "memory")
; #define PG8_WAIT_L(n) asm volatile("s_waitcnt lgkmcnt(" #n ")" ::: "memory")
; #define PG8_BAR __builtin_amdgcn_s_barrier()
; #define PG8_SCHED __builtin_amdgcn_sched_barrier(0)
; template <bool ALIGN_EPI, class Epi, class Sched>
; __device__ __forceinline__ void gemm_phase(LAS unsigned char* lds, const int lda, const int ldb, const int K, const Sched& S, const Epi& E, const size_t kstepA = (size_t)(BK * 2), const size_t kstepB = (size_t)(BK * 2)) {
;     ...
;             PG8_LDA(At, 1, 1); PG8_STAGE(PG8_SB(1, 0), b3, voffB); PG8_STAGE(PG8_SB(1, 1), b3 + hstepB, voffB); PG8_STAGE(PG8_SA(1, 0), a3, voffA);
;             PG8_WAIT_V(8); PG8_WAIT_L(0); PG8_BAR; PG8_MMA(1, 0, At, B0); PG8_MMA(1, 1, At, B1); PG8_BAR; PG8_SCHED;
;         }
;         if constexpr (ALIGN_EPI) { if (wr == 0) PG8_BAR; }
	s_mov_b32 m0, s56
	v_lshl_add_u64 v[222:223], v[222:223], 0, s[8:9]
	s_add_u32 s14, s14, 0x80080
	ds_read_b128 v[190:193], v148 offset:49152
	ds_read_b128 v[194:197], v148 offset:50176
	ds_read_b128 v[198:201], v148 offset:51200
	ds_read_b128 v[202:205], v148 offset:52224
	ds_read_b128 v[206:209], v148 offset:53248
	ds_read_b128 v[210:213], v148 offset:54272
	ds_read_b128 v[214:217], v148 offset:55296
	ds_read_b128 v[218:221], v148 offset:56320
	global_load_lds_dwordx4 v[222:223], off
	v_lshl_add_u64 v[222:223], v[224:225], 0, s[8:9]
	s_mov_b32 m0, s57
	s_addc_u32 s15, s15, 0
	global_load_lds_dwordx4 v[222:223], off
	v_lshl_add_u64 v[222:223], s[14:15], 0, v[136:137]
	s_mov_b32 m0, s58
	s_nop 0
	global_load_lds_dwordx4 v[222:223], off
	v_lshl_add_u64 v[222:223], s[14:15], 0, v[132:133]
	s_mov_b32 m0, s59
	s_nop 0
	global_load_lds_dwordx4 v[222:223], off
	v_lshl_add_u64 v[222:223], v[226:227], 0, s[8:9]
	s_mov_b32 m0, s33
	s_nop 0
	global_load_lds_dwordx4 v[222:223], off
	v_lshl_add_u64 v[222:223], v[228:229], 0, s[8:9]
	s_mov_b32 m0, s42
	s_nop 0
	global_load_lds_dwordx4 v[222:223], off
	s_waitcnt vmcnt(8)
	s_waitcnt lgkmcnt(0)
	s_barrier
	s_waitcnt lgkmcnt(0)
	v_mfma_f32_16x16x32_bf16 v[60:63], v[152:155], v[190:193], v[60:63]
	v_mfma_f32_16x16x32_bf16 v[60:63], v[156:159], v[194:197], v[60:63]
	v_mfma_f32_16x16x32_bf16 v[56:59], v[160:163], v[190:193], v[56:59]
	v_mfma_f32_16x16x32_bf16 v[56:59], v[164:167], v[194:197], v[56:59]
	v_mfma_f32_16x16x32_bf16 v[52:55], v[152:155], v[198:201], v[52:55]
	v_mfma_f32_16x16x32_bf16 v[52:55], v[156:159], v[202:205], v[52:55]
	v_mfma_f32_16x16x32_bf16 v[48:51], v[160:163], v[198:201], v[48:51]
	v_mfma_f32_16x16x32_bf16 v[48:51], v[164:167], v[202:205], v[48:51]
	v_mfma_f32_16x16x32_bf16 v[36:39], v[152:155], v[206:209], v[36:39]
	v_mfma_f32_16x16x32_bf16 v[36:39], v[156:159], v[210:213], v[36:39]
	v_mfma_f32_16x16x32_bf16 v[32:35], v[160:163], v[206:209], v[32:35]
	v_mfma_f32_16x16x32_bf16 v[32:35], v[164:167], v[210:213], v[32:35]
	v_mfma_f32_16x16x32_bf16 v[20:23], v[152:155], v[214:217], v[20:23]
	v_mfma_f32_16x16x32_bf16 v[20:23], v[156:159], v[218:221], v[20:23]
	v_mfma_f32_16x16x32_bf16 v[16:19], v[160:163], v[214:217], v[16:19]
	v_mfma_f32_16x16x32_bf16 v[16:19], v[164:167], v[218:221], v[16:19]
	v_mfma_f32_16x16x32_bf16 v[44:47], v[168:171], v[190:193], v[44:47]
	v_mfma_f32_16x16x32_bf16 v[44:47], v[172:175], v[194:197], v[44:47]
	v_mfma_f32_16x16x32_bf16 v[40:43], v[176:179], v[190:193], v[40:43]
	v_mfma_f32_16x16x32_bf16 v[40:43], v[180:183], v[194:197], v[40:43]
	v_mfma_f32_16x16x32_bf16 v[28:31], v[168:171], v[198:201], v[28:31]
	v_mfma_f32_16x16x32_bf16 v[28:31], v[172:175], v[202:205], v[28:31]
	v_mfma_f32_16x16x32_bf16 v[24:27], v[176:179], v[198:201], v[24:27]
	v_mfma_f32_16x16x32_bf16 v[24:27], v[180:183], v[202:205], v[24:27]
	v_mfma_f32_16x16x32_bf16 v[12:15], v[168:171], v[206:209], v[12:15]
	v_mfma_f32_16x16x32_bf16 v[12:15], v[172:175], v[210:213], v[12:15]
	v_mfma_f32_16x16x32_bf16 v[8:11], v[176:179], v[206:209], v[8:11]
	v_mfma_f32_16x16x32_bf16 v[8:11], v[180:183], v[210:213], v[8:11]
	v_mfma_f32_16x16x32_bf16 v[4:7], v[168:171], v[214:217], v[4:7]
	v_mfma_f32_16x16x32_bf16 v[4:7], v[172:175], v[218:221], v[4:7]
	v_mfma_f32_16x16x32_bf16 v[0:3], v[176:179], v[214:217], v[0:3]
	v_mfma_f32_16x16x32_bf16 v[0:3], v[180:183], v[218:221], v[0:3]
	s_barrier
	s_add_i32 s47, s47, 2
	s_add_u32 s12, s12, 0x100
	s_addc_u32 s13, s13, 0
	s_cmp_gt_u32 s47, 5
	s_cbranch_scc0 .LBB0_586
	s_cmpk_lt_u32 s18, 0x100
	s_cbranch_scc0 .LBB0_589
	s_barrier

; #define PG8_STAGE(bufoff, gbase, voff) do { _Pragma("unroll") for (int _i = 0; _i < 2; ++_i) \
;         __builtin_amdgcn_global_load_lds((const unsigned*)((const char*)(gbase) + (voff)[_i]), (LAS unsigned*)(lds + (bufoff) + ldsw + _i * 8192), 16, 0, 0); } while (0)
; #define PG8_LDA(dst, b, h) do { _Pragma("unroll") for (int m = 0; m < 4; ++m) _Pragma("unroll") for (int k = 0; k < 2; ++k) dst[m][k] = *(const LAS bf16x8*)(lds + PG8_SA(b, h) + aoff + m * 2048 + k * 1024); } while (0)
; #define PG8_LDB(dst, b, h) do { _Pragma("unroll") for (int n = 0; n < 2; ++n) _Pragma("unroll") for (int k = 0; k < 2; ++k) dst[n][k] = *(const LAS bf16x8*)(lds + PG8_SB(b, h) + boff + n * 2048 + k * 1024); } while (0)
; #define PG8_MMA(ai, bj, At, Bt) do { __builtin_amdgcn_s_setprio(1); _Pragma("unroll") for (int m = 0; m < 4; ++m) _Pragma("unroll") for (int n = 0; n < 2; ++n) _Pragma("unroll") for (int k = 0; k < 2; ++k) \
;         acc[ai][bj][m][n] = __builtin_amdgcn_mfma_f32_16x16x32_bf16(Bt[n][k], At[m][k], acc[ai][bj][m][n], 0, 0, 0); __builtin_amdgcn_s_setprio(0); } while (0)
; #define PG8_WAIT_V(n) asm volatile("s_waitcnt vmcnt(" #n ")" ::: "memory")
; #define PG8_WAIT_L(n) asm volatile("s_waitcnt lgkmcnt(" #n ")" ::: "memory")
; #define PG8_BAR __builtin_amdgcn_s_barrier()
; #define PG8_SCHED __builtin_amdgcn_sched_barrier(0)
; template <bool ALIGN_EPI, class Epi, class Sched>
; __device__ __forceinline__ void gemm_phase(LAS unsigned char* lds, const int lda, const int ldb, const int K, const Sched& S, const Epi& E, const size_t kstepA = (size_t)(BK * 2), const size_t kstepB = (size_t)(BK * 2)) {
;     ...
;             const char* a1 = cA + (size_t)(t + 1) * kstepA;
;             const char* a2 = last ? nA : cA + (size_t)(t + 2) * kstepA; const char* b2 = last ? nB : cB + (size_t)(t + 2) * kstep;
;             const char* a3 = a2 + kstepA; const char* b3 = b2 + kstep;
;             PG8_LDB(B0, 0, 0); PG8_LDB(B1, 0, 1); PG8_SCHED; PG8_LDA(At, 0, 0); PG8_STAGE(PG8_SA(1, 1), a1 + hstepA, voffA);
;             PG8_WAIT_V(8); PG8_WAIT_L(0); PG8_BAR; PG8_MMA(0, 0, At, B0); PG8_MMA(0, 1, At, B1); PG8_BAR; PG8_SCHED;
;             PG8_LDA(At, 0, 1); PG8_STAGE(PG8_SB(0, 0), b2, voffB); PG8_STAGE(PG8_SB(0, 1), b2 + hstepB, voffB); PG8_STAGE(PG8_SA(0, 0), a2, voffA);
;             PG8_WAIT_V(8); PG8_WAIT_L(0); PG8_BAR; PG8_MMA(1, 0, At, B0); PG8_MMA(1, 1, At, B1); PG8_BAR; PG8_SCHED;
.LBB0_594:
	ds_read_b128 v[152:155], v146
	ds_read_b128 v[156:159], v146 offset:1024
	ds_read_b128 v[160:163], v146 offset:2048
	ds_read_b128 v[164:167], v146 offset:3072
	ds_read_b128 v[168:171], v147
	ds_read_b128 v[172:175], v147 offset:1024
	ds_read_b128 v[176:179], v147 offset:2048
	ds_read_b128 v[180:183], v147 offset:3072
	s_add_u32 s14, s10, s12
	s_addc_u32 s15, s11, s13
	s_add_u32 s14, s14, 0xc414100
	s_addc_u32 s15, s15, 0
	s_add_u32 s63, s50, s12
	s_addc_u32 s64, s51, s13
	s_cmpk_eq_i32 s12, 0x300
	s_cselect_b32 s17, s1, s15
	s_cselect_b32 s16, s0, s14
	s_cselect_b32 s15, s7, s64
	s_cselect_b32 s14, s6, s63
	s_mov_b32 m0, s53
	v_lshl_add_u64 v[222:223], v[140:141], 0, s[12:13]
	ds_read_b128 v[190:193], v148
	ds_read_b128 v[194:197], v148 offset:1024
	ds_read_b128 v[198:201], v148 offset:2048
	ds_read_b128 v[202:205], v148 offset:3072
	ds_read_b128 v[206:209], v148 offset:4096
	ds_read_b128 v[210:213], v148 offset:5120
	ds_read_b128 v[214:217], v148 offset:6144
	ds_read_b128 v[218:221], v148 offset:7168
	global_load_lds_dwordx4 v[222:223], off
	v_lshl_add_u64 v[222:223], v[142:143], 0, s[12:13]
	s_mov_b32 m0, s54
	s_nop 0
	global_load_lds_dwordx4 v[222:223], off
	s_waitcnt vmcnt(8)
	s_waitcnt lgkmcnt(0)
	s_barrier
	s_waitcnt lgkmcnt(0)
	v_mfma_f32_16x16x32_bf16 v[124:127], v[152:155], v[190:193], v[124:127]
	v_mfma_f32_16x16x32_bf16 v[124:127], v[156:159], v[194:197], v[124:127]
	v_mfma_f32_16x16x32_bf16 v[120:123], v[160:163], v[190:193], v[120:123]
	v_mfma_f32_16x16x32_bf16 v[120:123], v[164:167], v[194:197], v[120:123]
	v_mfma_f32_16x16x32_bf16 v[116:119], v[152:155], v[198:201], v[116:119]
	v_mfma_f32_16x16x32_bf16 v[116:119], v[156:159], v[202:205], v[116:119]
	v_mfma_f32_16x16x32_bf16 v[108:111], v[160:163], v[198:201], v[108:111]
	v_mfma_f32_16x16x32_bf16 v[108:111], v[164:167], v[202:205], v[108:111]
	v_mfma_f32_16x16x32_bf16 v[100:103], v[152:155], v[206:209], v[100:103]
	v_mfma_f32_16x16x32_bf16 v[100:103], v[156:159], v[210:213], v[100:103]
	v_mfma_f32_16x16x32_bf16 v[96:99], v[160:163], v[206:209], v[96:99]
	v_mfma_f32_16x16x32_bf16 v[96:99], v[164:167], v[210:213], v[96:99]
	v_mfma_f32_16x16x32_bf16 v[84:87], v[152:155], v[214:217], v[84:87]
	v_mfma_f32_16x16x32_bf16 v[84:87], v[156:159], v[218:221], v[84:87]
	v_mfma_f32_16x16x32_bf16 v[80:83], v[160:163], v[214:217], v[80:83]
	v_mfma_f32_16x16x32_bf16 v[80:83], v[164:167], v[218:221], v[80:83]
	v_mfma_f32_16x16x32_bf16 v[112:115], v[168:171], v[190:193], v[112:115]
	v_mfma_f32_16x16x32_bf16 v[112:115], v[172:175], v[194:197], v[112:115]
	v_mfma_f32_16x16x32_bf16 v[104:107], v[176:179], v[190:193], v[104:107]
	v_mfma_f32_16x16x32_bf16 v[104:107], v[180:183], v[194:197], v[104:107]
	v_mfma_f32_16x16x32_bf16 v[92:95], v[168:171], v[198:201], v[92:95]
	v_mfma_f32_16x16x32_bf16 v[92:95], v[172:175], v[202:205], v[92:95]
	v_mfma_f32_16x16x32_bf16 v[88:91], v[176:179], v[198:201], v[88:91]
	v_mfma_f32_16x16x32_bf16 v[88:91], v[180:183], v[202:205], v[88:91]
	v_mfma_f32_16x16x32_bf16 v[76:79], v[168:171], v[206:209], v[76:79]
	v_mfma_f32_16x16x32_bf16 v[76:79], v[172:175], v[210:213], v[76:79]
	v_mfma_f32_16x16x32_bf16 v[72:75], v[176:179], v[206:209], v[72:75]
	v_mfma_f32_16x16x32_bf16 v[72:75], v[180:183], v[210:213], v[72:75]
	v_mfma_f32_16x16x32_bf16 v[68:71], v[168:171], v[214:217], v[68:71]
	v_mfma_f32_16x16x32_bf16 v[68:71], v[172:175], v[218:221], v[68:71]
	v_mfma_f32_16x16x32_bf16 v[64:67], v[176:179], v[214:217], v[64:67]
	v_mfma_f32_16x16x32_bf16 v[64:67], v[180:183], v[218:221], v[64:67]
	s_barrier
	s_mov_b32 m0, s55
	v_lshl_add_u64 v[222:223], s[14:15], 0, v[136:137]
	s_add_u32 s64, s14, 0x20000
	ds_read_b128 v[190:193], v148 offset:16384
	ds_read_b128 v[194:197], v148 offset:17408
	ds_read_b128 v[198:201], v148 offset:18432
	ds_read_b128 v[202:205], v148 offset:19456
	ds_read_b128 v[206:209], v148 offset:20480
	ds_read_b128 v[210:213], v148 offset:21504
	ds_read_b128 v[214:217], v148 offset:22528
	ds_read_b128 v[218:221], v148 offset:23552
	global_load_lds_dwordx4 v[222:223], off
	v_lshl_add_u64 v[224:225], s[14:15], 0, v[132:133]
	s_mov_b32 m0, s56
	s_addc_u32 s65, s15, 0
	global_load_lds_dwordx4 v[224:225], off
	v_lshl_add_u64 v[226:227], s[64:65], 0, v[136:137]
	s_mov_b32 m0, s57
	v_lshl_add_u64 v[228:229], s[16:17], 0, v[134:135]
	global_load_lds_dwordx4 v[226:227], off
	v_lshl_add_u64 v[226:227], s[64:65], 0, v[132:133]
	s_mov_b32 m0, s58
	s_nop 0
	global_load_lds_dwordx4 v[226:227], off
	v_lshl_add_u64 v[226:227], s[16:17], 0, v[138:139]
	s_mov_b32 m0, s21
	s_nop 0
	global_load_lds_dwordx4 v[226:227], off
	s_mov_b32 m0, s22
	s_nop 0
	global_load_lds_dwordx4 v[228:229], off
	s_waitcnt vmcnt(8)
	s_waitcnt lgkmcnt(0)
	s_barrier
; #define PG8_STAGE(bufoff, gbase, voff) do { _Pragma("unroll") for (int _i = 0; _i < 2; ++_i) \
;         __builtin_amdgcn_global_load_lds((const unsigned*)((const char*)(gbase) + (voff)[_i]), (LAS unsigned*)(lds + (bufoff) + ldsw + _i * 8192), 16, 0, 0); } while (0)
; #define PG8_LDA(dst, b, h) do { _Pragma("unroll") for (int m = 0; m < 4; ++m) _Pragma("unroll") for (int k = 0; k < 2; ++k) dst[m][k] = *(const LAS bf16x8*)(lds + PG8_SA(b, h) + aoff + m * 2048 + k * 1024); } while (0)
; #define PG8_LDB(dst, b, h) do { _Pragma("unroll") for (int n = 0; n < 2; ++n) _Pragma("unroll") for (int k = 0; k < 2; ++k) dst[n][k] = *(const LAS bf16x8*)(lds + PG8_SB(b, h) + boff + n * 2048 + k * 1024); } while (0)
; #define PG8_MMA(ai, bj, At, Bt) do { __builtin_amdgcn_s_setprio(1); _Pragma("unroll") for (int m = 0; m < 4; ++m) _Pragma("unroll") for (int n = 0; n < 2; ++n) _Pragma("unroll") for (int k = 0; k < 2; ++k) \
;         acc[ai][bj][m][n] = __builtin_amdgcn_mfma_f32_16x16x32_bf16(Bt[n][k], At[m][k], acc[ai][bj][m][n], 0, 0, 0); __builtin_amdgcn_s_setprio(0); } while (0)
; #define PG8_WAIT_V(n) asm volatile("s_waitcnt vmcnt(" #n ")" ::: "memory")
; #define PG8_WAIT_L(n) asm volatile("s_waitcnt lgkmcnt(" #n ")" ::: "memory")
; #define PG8_BAR __builtin_amdgcn_s_barrier()
; #define PG8_SCHED __builtin_amdgcn_sched_barrier(0)
; template <bool ALIGN_EPI, class Epi, class Sched>
; __device__ __forceinline__ void gemm_phase(LAS unsigned char* lds, const int lda, const int ldb, const int K, const Sched& S, const Epi& E, const size_t kstepA = (size_t)(BK * 2), const size_t kstepB = (size_t)(BK * 2)) {
;     ...
;             PG8_WAIT_V(8); PG8_WAIT_L(0); PG8_BAR; PG8_MMA(1, 0, At, B0); PG8_MMA(1, 1, At, B1); PG8_BAR; PG8_SCHED;
;             PG8_LDB(B0, 1, 0); PG8_LDB(B1, 1, 1); PG8_SCHED; PG8_LDA(At, 1, 0); PG8_STAGE(PG8_SA(0, 1), a2 + hstepA, voffA);
;             PG8_WAIT_V(8); PG8_WAIT_L(0); PG8_BAR; PG8_MMA(0, 0, At, B0); PG8_MMA(0, 1, At, B1); PG8_BAR; PG8_SCHED;
	s_waitcnt lgkmcnt(0)
	v_mfma_f32_16x16x32_bf16 v[60:63], v[152:155], v[190:193], v[60:63]
	v_mfma_f32_16x16x32_bf16 v[60:63], v[156:159], v[194:197], v[60:63]
	v_mfma_f32_16x16x32_bf16 v[56:59], v[160:163], v[190:193], v[56:59]
	v_mfma_f32_16x16x32_bf16 v[56:59], v[164:167], v[194:197], v[56:59]
	v_mfma_f32_16x16x32_bf16 v[52:55], v[152:155], v[198:201], v[52:55]
	v_mfma_f32_16x16x32_bf16 v[52:55], v[156:159], v[202:205], v[52:55]
	v_mfma_f32_16x16x32_bf16 v[48:51], v[160:163], v[198:201], v[48:51]
	v_mfma_f32_16x16x32_bf16 v[48:51], v[164:167], v[202:205], v[48:51]
	v_mfma_f32_16x16x32_bf16 v[36:39], v[152:155], v[206:209], v[36:39]
	v_mfma_f32_16x16x32_bf16 v[36:39], v[156:159], v[210:213], v[36:39]
	v_mfma_f32_16x16x32_bf16 v[32:35], v[160:163], v[206:209], v[32:35]
	v_mfma_f32_16x16x32_bf16 v[32:35], v[164:167], v[210:213], v[32:35]
	v_mfma_f32_16x16x32_bf16 v[20:23], v[152:155], v[214:217], v[20:23]
	v_mfma_f32_16x16x32_bf16 v[20:23], v[156:159], v[218:221], v[20:23]
	v_mfma_f32_16x16x32_bf16 v[16:19], v[160:163], v[214:217], v[16:19]
	v_mfma_f32_16x16x32_bf16 v[16:19], v[164:167], v[218:221], v[16:19]
	v_mfma_f32_16x16x32_bf16 v[44:47], v[168:171], v[190:193], v[44:47]
	v_mfma_f32_16x16x32_bf16 v[44:47], v[172:175], v[194:197], v[44:47]
	v_mfma_f32_16x16x32_bf16 v[40:43], v[176:179], v[190:193], v[40:43]
	v_mfma_f32_16x16x32_bf16 v[40:43], v[180:183], v[194:197], v[40:43]
	v_mfma_f32_16x16x32_bf16 v[28:31], v[168:171], v[198:201], v[28:31]
	v_mfma_f32_16x16x32_bf16 v[28:31], v[172:175], v[202:205], v[28:31]
	v_mfma_f32_16x16x32_bf16 v[24:27], v[176:179], v[198:201], v[24:27]
	v_mfma_f32_16x16x32_bf16 v[24:27], v[180:183], v[202:205], v[24:27]
	v_mfma_f32_16x16x32_bf16 v[12:15], v[168:171], v[206:209], v[12:15]
	v_mfma_f32_16x16x32_bf16 v[12:15], v[172:175], v[210:213], v[12:15]
	v_mfma_f32_16x16x32_bf16 v[8:11], v[176:179], v[206:209], v[8:11]
	v_mfma_f32_16x16x32_bf16 v[8:11], v[180:183], v[210:213], v[8:11]
	v_mfma_f32_16x16x32_bf16 v[4:7], v[168:171], v[214:217], v[4:7]
	v_mfma_f32_16x16x32_bf16 v[4:7], v[172:175], v[218:221], v[4:7]
	v_mfma_f32_16x16x32_bf16 v[0:3], v[176:179], v[214:217], v[0:3]
	v_mfma_f32_16x16x32_bf16 v[0:3], v[180:183], v[218:221], v[0:3]
	s_barrier
	ds_read_b128 v[152:155], v149
	ds_read_b128 v[156:159], v149 offset:1024
	ds_read_b128 v[160:163], v149 offset:2048
	ds_read_b128 v[164:167], v149 offset:3072
	ds_read_b128 v[168:171], v150
	ds_read_b128 v[172:175], v150 offset:1024
	ds_read_b128 v[176:179], v150 offset:2048
	ds_read_b128 v[180:183], v150 offset:3072
	s_add_u32 s16, s16, 0x80000
	s_addc_u32 s17, s17, 0
	s_mov_b32 m0, s33
	v_lshl_add_u64 v[230:231], s[16:17], 0, v[138:139]
	ds_read_b128 v[190:193], v148 offset:32768
	ds_read_b128 v[194:197], v148 offset:33792
	ds_read_b128 v[198:201], v148 offset:34816
	ds_read_b128 v[202:205], v148 offset:35840
	ds_read_b128 v[206:209], v148 offset:36864
	ds_read_b128 v[210:213], v148 offset:37888
	ds_read_b128 v[214:217], v148 offset:38912
	ds_read_b128 v[218:221], v148 offset:39936
	global_load_lds_dwordx4 v[230:231], off
	v_lshl_add_u64 v[230:231], s[16:17], 0, v[134:135]
	s_mov_b32 m0, s42
	s_nop 0
	global_load_lds_dwordx4 v[230:231], off
	s_waitcnt vmcnt(8)
	s_waitcnt lgkmcnt(0)
	s_barrier
	s_waitcnt lgkmcnt(0)
	v_mfma_f32_16x16x32_bf16 v[124:127], v[152:155], v[190:193], v[124:127]
	v_mfma_f32_16x16x32_bf16 v[124:127], v[156:159], v[194:197], v[124:127]
	v_mfma_f32_16x16x32_bf16 v[120:123], v[160:163], v[190:193], v[120:123]
	v_mfma_f32_16x16x32_bf16 v[120:123], v[164:167], v[194:197], v[120:123]
	v_mfma_f32_16x16x32_bf16 v[116:119], v[152:155], v[198:201], v[116:119]
	v_mfma_f32_16x16x32_bf16 v[116:119], v[156:159], v[202:205], v[116:119]
	v_mfma_f32_16x16x32_bf16 v[108:111], v[160:163], v[198:201], v[108:111]
	v_mfma_f32_16x16x32_bf16 v[108:111], v[164:167], v[202:205], v[108:111]
	v_mfma_f32_16x16x32_bf16 v[100:103], v[152:155], v[206:209], v[100:103]
	v_mfma_f32_16x16x32_bf16 v[100:103], v[156:159], v[210:213], v[100:103]
	v_mfma_f32_16x16x32_bf16 v[96:99], v[160:163], v[206:209], v[96:99]
	v_mfma_f32_16x16x32_bf16 v[96:99], v[164:167], v[210:213], v[96:99]
	v_mfma_f32_16x16x32_bf16 v[84:87], v[152:155], v[214:217], v[84:87]
	v_mfma_f32_16x16x32_bf16 v[84:87], v[156:159], v[218:221], v[84:87]
	v_mfma_f32_16x16x32_bf16 v[80:83], v[160:163], v[214:217], v[80:83]
	v_mfma_f32_16x16x32_bf16 v[80:83], v[164:167], v[218:221], v[80:83]
	v_mfma_f32_16x16x32_bf16 v[112:115], v[168:171], v[190:193], v[112:115]
	v_mfma_f32_16x16x32_bf16 v[112:115], v[172:175], v[194:197], v[112:115]
	v_mfma_f32_16x16x32_bf16 v[104:107], v[176:179], v[190:193], v[104:107]
	v_mfma_f32_16x16x32_bf16 v[104:107], v[180:183], v[194:197], v[104:107]
	v_mfma_f32_16x16x32_bf16 v[92:95], v[168:171], v[198:201], v[92:95]
	v_mfma_f32_16x16x32_bf16 v[92:95], v[172:175], v[202:205], v[92:95]
	v_mfma_f32_16x16x32_bf16 v[88:91], v[176:179], v[198:201], v[88:91]
	v_mfma_f32_16x16x32_bf16 v[88:91], v[180:183], v[202:205], v[88:91]
	v_mfma_f32_16x16x32_bf16 v[76:79], v[168:171], v[206:209], v[76:79]
	v_mfma_f32_16x16x32_bf16 v[76:79], v[172:175], v[210:213], v[76:79]
	v_mfma_f32_16x16x32_bf16 v[72:75], v[176:179], v[206:209], v[72:75]
	v_mfma_f32_16x16x32_bf16 v[72:75], v[180:183], v[210:213], v[72:75]
	v_mfma_f32_16x16x32_bf16 v[68:71], v[168:171], v[214:217], v[68:71]
	v_mfma_f32_16x16x32_bf16 v[68:71], v[172:175], v[218:221], v[68:71]
	v_mfma_f32_16x16x32_bf16 v[64:67], v[176:179], v[214:217], v[64:67]
	v_mfma_f32_16x16x32_bf16 v[64:67], v[180:183], v[218:221], v[64:67]
	s_barrier
; #define PG8_STAGE(bufoff, gbase, voff) do { _Pragma("unroll") for (int _i = 0; _i < 2; ++_i) \
;         __builtin_amdgcn_global_load_lds((const unsigned*)((const char*)(gbase) + (voff)[_i]), (LAS unsigned*)(lds + (bufoff) + ldsw + _i * 8192), 16, 0, 0); } while (0)
; #define PG8_LDA(dst, b, h) do { _Pragma("unroll") for (int m = 0; m < 4; ++m) _Pragma("unroll") for (int k = 0; k < 2; ++k) dst[m][k] = *(const LAS bf16x8*)(lds + PG8_SA(b, h) + aoff + m * 2048 + k * 1024); } while (0)
; #define PG8_MMA(ai, bj, At, Bt) do { __builtin_amdgcn_s_setprio(1); _Pragma("unroll") for (int m = 0; m < 4; ++m) _Pragma("unroll") for (int n = 0; n < 2; ++n) _Pragma("unroll") for (int k = 0; k < 2; ++k) \
;         acc[ai][bj][m][n] = __builtin_amdgcn_mfma_f32_16x16x32_bf16(Bt[n][k], At[m][k], acc[ai][bj][m][n], 0, 0, 0); __builtin_amdgcn_s_setprio(0); } while (0)
; #define PG8_WAIT_V(n) asm volatile("s_waitcnt vmcnt(" #n ")" ::: "memory")
; #define PG8_WAIT_L(n) asm volatile("s_waitcnt lgkmcnt(" #n ")" ::: "memory")
; #define PG8_BAR __builtin_amdgcn_s_barrier()
; #define PG8_SCHED __builtin_amdgcn_sched_barrier(0)
; template <bool ALIGN_EPI, class Epi, class Sched>
; __device__ __forceinline__ void gemm_phase(LAS unsigned char* lds, const int lda, const int ldb, const int K, const Sched& S, const Epi& E, const size_t kstepA = (size_t)(BK * 2), const size_t kstepB = (size_t)(BK * 2)) {
;     ...
;             PG8_LDA(At, 1, 1); PG8_STAGE(PG8_SB(1, 0), b3, voffB); PG8_STAGE(PG8_SB(1, 1), b3 + hstepB, voffB); PG8_STAGE(PG8_SA(1, 0), a3, voffA);
;             PG8_WAIT_V(8); PG8_WAIT_L(0); PG8_BAR; PG8_MMA(1, 0, At, B0); PG8_MMA(1, 1, At, B1); PG8_BAR; PG8_SCHED;
;         }
;         if constexpr (ALIGN_EPI) { if (wr == 0) PG8_BAR; }
	s_mov_b32 m0, s59
	v_lshl_add_u64 v[222:223], v[222:223], 0, s[8:9]
	s_add_u32 s14, s14, 0x20080
	ds_read_b128 v[190:193], v148 offset:49152
	ds_read_b128 v[194:197], v148 offset:50176
	ds_read_b128 v[198:201], v148 offset:51200
	ds_read_b128 v[202:205], v148 offset:52224
	ds_read_b128 v[206:209], v148 offset:53248
	ds_read_b128 v[210:213], v148 offset:54272
	ds_read_b128 v[214:217], v148 offset:55296
	ds_read_b128 v[218:221], v148 offset:56320
	global_load_lds_dwordx4 v[222:223], off
	v_lshl_add_u64 v[222:223], v[224:225], 0, s[8:9]
	s_mov_b32 m0, s60
	s_addc_u32 s15, s15, 0
	global_load_lds_dwordx4 v[222:223], off
	v_lshl_add_u64 v[222:223], s[14:15], 0, v[136:137]
	s_mov_b32 m0, s61
	s_nop 0
	global_load_lds_dwordx4 v[222:223], off
	v_lshl_add_u64 v[222:223], s[14:15], 0, v[132:133]
	s_mov_b32 m0, s62
	s_nop 0
	global_load_lds_dwordx4 v[222:223], off
	v_lshl_add_u64 v[222:223], v[226:227], 0, s[8:9]
	s_mov_b32 m0, s46
	s_nop 0
	global_load_lds_dwordx4 v[222:223], off
	v_lshl_add_u64 v[222:223], v[228:229], 0, s[8:9]
	s_mov_b32 m0, s47
	s_nop 0
	global_load_lds_dwordx4 v[222:223], off
	s_waitcnt vmcnt(8)
	s_waitcnt lgkmcnt(0)
	s_barrier
	s_waitcnt lgkmcnt(0)
	v_mfma_f32_16x16x32_bf16 v[60:63], v[152:155], v[190:193], v[60:63]
	v_mfma_f32_16x16x32_bf16 v[60:63], v[156:159], v[194:197], v[60:63]
	v_mfma_f32_16x16x32_bf16 v[56:59], v[160:163], v[190:193], v[56:59]
	v_mfma_f32_16x16x32_bf16 v[56:59], v[164:167], v[194:197], v[56:59]
	v_mfma_f32_16x16x32_bf16 v[52:55], v[152:155], v[198:201], v[52:55]
	v_mfma_f32_16x16x32_bf16 v[52:55], v[156:159], v[202:205], v[52:55]
	v_mfma_f32_16x16x32_bf16 v[48:51], v[160:163], v[198:201], v[48:51]
	v_mfma_f32_16x16x32_bf16 v[48:51], v[164:167], v[202:205], v[48:51]
	v_mfma_f32_16x16x32_bf16 v[36:39], v[152:155], v[206:209], v[36:39]
	v_mfma_f32_16x16x32_bf16 v[36:39], v[156:159], v[210:213], v[36:39]
	v_mfma_f32_16x16x32_bf16 v[32:35], v[160:163], v[206:209], v[32:35]
	v_mfma_f32_16x16x32_bf16 v[32:35], v[164:167], v[210:213], v[32:35]
	v_mfma_f32_16x16x32_bf16 v[20:23], v[152:155], v[214:217], v[20:23]
	v_mfma_f32_16x16x32_bf16 v[20:23], v[156:159], v[218:221], v[20:23]
	v_mfma_f32_16x16x32_bf16 v[16:19], v[160:163], v[214:217], v[16:19]
	v_mfma_f32_16x16x32_bf16 v[16:19], v[164:167], v[218:221], v[16:19]
	v_mfma_f32_16x16x32_bf16 v[44:47], v[168:171], v[190:193], v[44:47]
	v_mfma_f32_16x16x32_bf16 v[44:47], v[172:175], v[194:197], v[44:47]
	v_mfma_f32_16x16x32_bf16 v[40:43], v[176:179], v[190:193], v[40:43]
	v_mfma_f32_16x16x32_bf16 v[40:43], v[180:183], v[194:197], v[40:43]
	v_mfma_f32_16x16x32_bf16 v[28:31], v[168:171], v[198:201], v[28:31]
	v_mfma_f32_16x16x32_bf16 v[28:31], v[172:175], v[202:205], v[28:31]
	v_mfma_f32_16x16x32_bf16 v[24:27], v[176:179], v[198:201], v[24:27]
	v_mfma_f32_16x16x32_bf16 v[24:27], v[180:183], v[202:205], v[24:27]
	v_mfma_f32_16x16x32_bf16 v[12:15], v[168:171], v[206:209], v[12:15]
	v_mfma_f32_16x16x32_bf16 v[12:15], v[172:175], v[210:213], v[12:15]
	v_mfma_f32_16x16x32_bf16 v[8:11], v[176:179], v[206:209], v[8:11]
	v_mfma_f32_16x16x32_bf16 v[8:11], v[180:183], v[210:213], v[8:11]
	v_mfma_f32_16x16x32_bf16 v[4:7], v[168:171], v[214:217], v[4:7]
	v_mfma_f32_16x16x32_bf16 v[4:7], v[172:175], v[218:221], v[4:7]
	v_mfma_f32_16x16x32_bf16 v[0:3], v[176:179], v[214:217], v[0:3]
	v_mfma_f32_16x16x32_bf16 v[0:3], v[180:183], v[218:221], v[0:3]
	s_barrier
	s_add_i32 s52, s52, 2
	s_add_u32 s12, s12, 0x100
	s_addc_u32 s13, s13, 0
	s_cmp_gt_u32 s52, 5
	s_cbranch_scc0 .LBB0_594
	s_cmpk_lt_u32 s18, 0x100
	s_cbranch_scc0 .LBB0_597
	s_barrier

; #define PG8_STAGE(bufoff, gbase, voff) do { _Pragma("unroll") for (int _i = 0; _i < 2; ++_i) \
;         __builtin_amdgcn_global_load_lds((const unsigned*)((const char*)(gbase) + (voff)[_i]), (LAS unsigned*)(lds + (bufoff) + ldsw + _i * 8192), 16, 0, 0); } while (0)
; #define PG8_LDA(dst, b, h) do { _Pragma("unroll") for (int m = 0; m < 4; ++m) _Pragma("unroll") for (int k = 0; k < 2; ++k) dst[m][k] = *(const LAS bf16x8*)(lds + PG8_SA(b, h) + aoff + m * 2048 + k * 1024); } while (0)
; #define PG8_LDB(dst, b, h) do { _Pragma("unroll") for (int n = 0; n < 2; ++n) _Pragma("unroll") for (int k = 0; k < 2; ++k) dst[n][k] = *(const LAS bf16x8*)(lds + PG8_SB(b, h) + boff + n * 2048 + k * 1024); } while (0)
; #define PG8_MMA(ai, bj, At, Bt) do { __builtin_amdgcn_s_setprio(1); _Pragma("unroll") for (int m = 0; m < 4; ++m) _Pragma("unroll") for (int n = 0; n < 2; ++n) _Pragma("unroll") for (int k = 0; k < 2; ++k) \
;         acc[ai][bj][m][n] = __builtin_amdgcn_mfma_f32_16x16x32_bf16(Bt[n][k], At[m][k], acc[ai][bj][m][n], 0, 0, 0); __builtin_amdgcn_s_setprio(0); } while (0)
; #define PG8_WAIT_V(n) asm volatile("s_waitcnt vmcnt(" #n ")" ::: "memory")
; #define PG8_WAIT_L(n) asm volatile("s_waitcnt lgkmcnt(" #n ")" ::: "memory")
; #define PG8_BAR __builtin_amdgcn_s_barrier()
; #define PG8_SCHED __builtin_amdgcn_sched_barrier(0)
; template <bool ALIGN_EPI, class Epi, class Sched>
; __device__ __forceinline__ void gemm_phase(LAS unsigned char* lds, const int lda, const int ldb, const int K, const Sched& S, const Epi& E, const size_t kstepA = (size_t)(BK * 2), const size_t kstepB = (size_t)(BK * 2)) {
;     ...
;             const char* a1 = cA + (size_t)(t + 1) * kstepA;
;             const char* a2 = last ? nA : cA + (size_t)(t + 2) * kstepA; const char* b2 = last ? nB : cB + (size_t)(t + 2) * kstep;
;             const char* a3 = a2 + kstepA; const char* b3 = b2 + kstep;
;             PG8_LDB(B0, 0, 0); PG8_LDB(B1, 0, 1); PG8_SCHED; PG8_LDA(At, 0, 0); PG8_STAGE(PG8_SA(1, 1), a1 + hstepA, voffA);
;             PG8_WAIT_V(8); PG8_WAIT_L(0); PG8_BAR; PG8_MMA(0, 0, At, B0); PG8_MMA(0, 1, At, B1); PG8_BAR; PG8_SCHED;
;             PG8_LDA(At, 0, 1); PG8_STAGE(PG8_SB(0, 0), b2, voffB); PG8_STAGE(PG8_SB(0, 1), b2 + hstepB, voffB); PG8_STAGE(PG8_SA(0, 0), a2, voffA);
;             PG8_WAIT_V(8); PG8_WAIT_L(0); PG8_BAR; PG8_MMA(1, 0, At, B0); PG8_MMA(1, 1, At, B1); PG8_BAR; PG8_SCHED;
.LBB0_813:
	ds_read_b128 v[146:149], v140
	ds_read_b128 v[150:153], v140 offset:1024
	ds_read_b128 v[158:161], v140 offset:2048
	ds_read_b128 v[162:165], v140 offset:3072
	ds_read_b128 v[166:169], v141
	ds_read_b128 v[170:173], v141 offset:1024
	ds_read_b128 v[174:177], v141 offset:2048
	ds_read_b128 v[178:181], v141 offset:3072
	s_add_u32 s14, s8, s12
	s_addc_u32 s15, s9, s13
	s_cmp_eq_u32 s49, 28
	s_cselect_b32 s20, s8, s14
	s_cselect_b32 s21, s9, s15
	s_cselect_b32 s16, s10, s45
	s_cselect_b32 s17, s11, s48
	s_add_u32 s14, s20, 0x200000
	s_addc_u32 s15, s21, 0
	s_mov_b32 m0, s50
	v_lshl_add_u64 v[182:183], s[8:9], 0, v[136:137]
	ds_read_b128 v[186:189], v142
	ds_read_b128 v[190:193], v142 offset:1024
	ds_read_b128 v[194:197], v142 offset:2048
	ds_read_b128 v[198:201], v142 offset:3072
	ds_read_b128 v[202:205], v142 offset:4096
	ds_read_b128 v[206:209], v142 offset:5120
	ds_read_b128 v[210:213], v142 offset:6144
	ds_read_b128 v[214:217], v142 offset:7168
	global_load_lds_dwordx4 v[182:183], off
	v_lshl_add_u64 v[182:183], s[8:9], 0, v[138:139]
	s_mov_b32 m0, s51
	s_nop 0
	global_load_lds_dwordx4 v[182:183], off
	s_waitcnt vmcnt(8)
	s_waitcnt lgkmcnt(0)
	s_barrier
	s_waitcnt lgkmcnt(0)
	v_mfma_f32_16x16x32_bf16 v[124:127], v[146:149], v[186:189], v[124:127]
	v_mfma_f32_16x16x32_bf16 v[124:127], v[150:153], v[190:193], v[124:127]
	v_mfma_f32_16x16x32_bf16 v[120:123], v[158:161], v[186:189], v[120:123]
	v_mfma_f32_16x16x32_bf16 v[120:123], v[162:165], v[190:193], v[120:123]
	v_mfma_f32_16x16x32_bf16 v[108:111], v[146:149], v[194:197], v[108:111]
	v_mfma_f32_16x16x32_bf16 v[108:111], v[150:153], v[198:201], v[108:111]
	v_mfma_f32_16x16x32_bf16 v[104:107], v[158:161], v[194:197], v[104:107]
	v_mfma_f32_16x16x32_bf16 v[104:107], v[162:165], v[198:201], v[104:107]
	v_mfma_f32_16x16x32_bf16 v[92:95], v[146:149], v[202:205], v[92:95]
	v_mfma_f32_16x16x32_bf16 v[92:95], v[150:153], v[206:209], v[92:95]
	v_mfma_f32_16x16x32_bf16 v[88:91], v[158:161], v[202:205], v[88:91]
	v_mfma_f32_16x16x32_bf16 v[88:91], v[162:165], v[206:209], v[88:91]
	v_mfma_f32_16x16x32_bf16 v[76:79], v[146:149], v[210:213], v[76:79]
	v_mfma_f32_16x16x32_bf16 v[76:79], v[150:153], v[214:217], v[76:79]
	v_mfma_f32_16x16x32_bf16 v[72:75], v[158:161], v[210:213], v[72:75]
	v_mfma_f32_16x16x32_bf16 v[72:75], v[162:165], v[214:217], v[72:75]
	v_mfma_f32_16x16x32_bf16 v[116:119], v[166:169], v[186:189], v[116:119]
	v_mfma_f32_16x16x32_bf16 v[116:119], v[170:173], v[190:193], v[116:119]
	v_mfma_f32_16x16x32_bf16 v[112:115], v[174:177], v[186:189], v[112:115]
	v_mfma_f32_16x16x32_bf16 v[112:115], v[178:181], v[190:193], v[112:115]
	v_mfma_f32_16x16x32_bf16 v[100:103], v[166:169], v[194:197], v[100:103]
	v_mfma_f32_16x16x32_bf16 v[100:103], v[170:173], v[198:201], v[100:103]
	v_mfma_f32_16x16x32_bf16 v[96:99], v[174:177], v[194:197], v[96:99]
	v_mfma_f32_16x16x32_bf16 v[96:99], v[178:181], v[198:201], v[96:99]
	v_mfma_f32_16x16x32_bf16 v[84:87], v[166:169], v[202:205], v[84:87]
	v_mfma_f32_16x16x32_bf16 v[84:87], v[170:173], v[206:209], v[84:87]
	v_mfma_f32_16x16x32_bf16 v[80:83], v[174:177], v[202:205], v[80:83]
	v_mfma_f32_16x16x32_bf16 v[80:83], v[178:181], v[206:209], v[80:83]
	v_mfma_f32_16x16x32_bf16 v[68:71], v[166:169], v[210:213], v[68:71]
	v_mfma_f32_16x16x32_bf16 v[68:71], v[170:173], v[214:217], v[68:71]
	v_mfma_f32_16x16x32_bf16 v[64:67], v[174:177], v[210:213], v[64:67]
	v_mfma_f32_16x16x32_bf16 v[64:67], v[178:181], v[214:217], v[64:67]
	s_barrier
	s_mov_b32 m0, s52
	v_lshl_add_u64 v[182:183], s[16:17], 0, v[130:131]
	s_add_u32 s60, s16, 0x4000
	ds_read_b128 v[186:189], v142 offset:16384
	ds_read_b128 v[190:193], v142 offset:17408
	ds_read_b128 v[194:197], v142 offset:18432
	ds_read_b128 v[198:201], v142 offset:19456
	ds_read_b128 v[202:205], v142 offset:20480
	ds_read_b128 v[206:209], v142 offset:21504
	ds_read_b128 v[210:213], v142 offset:22528
	ds_read_b128 v[214:217], v142 offset:23552
	global_load_lds_dwordx4 v[182:183], off
	v_lshl_add_u64 v[182:183], s[16:17], 0, v[134:135]
	s_mov_b32 m0, s53
	s_addc_u32 s61, s17, 0
	global_load_lds_dwordx4 v[182:183], off
	v_lshl_add_u64 v[182:183], s[60:61], 0, v[130:131]
	s_mov_b32 m0, s54
	s_nop 0
	global_load_lds_dwordx4 v[182:183], off
	v_lshl_add_u64 v[182:183], s[60:61], 0, v[134:135]
	s_mov_b32 m0, s55
	s_nop 0
	global_load_lds_dwordx4 v[182:183], off
	v_lshl_add_u64 v[182:183], s[20:21], 0, v[128:129]
	s_mov_b32 m0, s1
	s_nop 0
	global_load_lds_dwordx4 v[182:183], off
	v_lshl_add_u64 v[182:183], s[20:21], 0, v[132:133]
	s_mov_b32 m0, s40
	s_nop 0
	global_load_lds_dwordx4 v[182:183], off
	s_waitcnt vmcnt(8)
	s_waitcnt lgkmcnt(0)
	s_barrier
; #define PG8_STAGE(bufoff, gbase, voff) do { _Pragma("unroll") for (int _i = 0; _i < 2; ++_i) \
;         __builtin_amdgcn_global_load_lds((const unsigned*)((const char*)(gbase) + (voff)[_i]), (LAS unsigned*)(lds + (bufoff) + ldsw + _i * 8192), 16, 0, 0); } while (0)
; #define PG8_LDA(dst, b, h) do { _Pragma("unroll") for (int m = 0; m < 4; ++m) _Pragma("unroll") for (int k = 0; k < 2; ++k) dst[m][k] = *(const LAS bf16x8*)(lds + PG8_SA(b, h) + aoff + m * 2048 + k * 1024); } while (0)
; #define PG8_LDB(dst, b, h) do { _Pragma("unroll") for (int n = 0; n < 2; ++n) _Pragma("unroll") for (int k = 0; k < 2; ++k) dst[n][k] = *(const LAS bf16x8*)(lds + PG8_SB(b, h) + boff + n * 2048 + k * 1024); } while (0)
; #define PG8_MMA(ai, bj, At, Bt) do { __builtin_amdgcn_s_setprio(1); _Pragma("unroll") for (int m = 0; m < 4; ++m) _Pragma("unroll") for (int n = 0; n < 2; ++n) _Pragma("unroll") for (int k = 0; k < 2; ++k) \
;         acc[ai][bj][m][n] = __builtin_amdgcn_mfma_f32_16x16x32_bf16(Bt[n][k], At[m][k], acc[ai][bj][m][n], 0, 0, 0); __builtin_amdgcn_s_setprio(0); } while (0)
; #define PG8_WAIT_V(n) asm volatile("s_waitcnt vmcnt(" #n ")" ::: "memory")
; #define PG8_WAIT_L(n) asm volatile("s_waitcnt lgkmcnt(" #n ")" ::: "memory")
; #define PG8_BAR __builtin_amdgcn_s_barrier()
; #define PG8_SCHED __builtin_amdgcn_sched_barrier(0)
; template <bool ALIGN_EPI, class Epi, class Sched>
; __device__ __forceinline__ void gemm_phase(LAS unsigned char* lds, const int lda, const int ldb, const int K, const Sched& S, const Epi& E, const size_t kstepA = (size_t)(BK * 2), const size_t kstepB = (size_t)(BK * 2)) {
;     ...
;             PG8_WAIT_V(8); PG8_WAIT_L(0); PG8_BAR; PG8_MMA(1, 0, At, B0); PG8_MMA(1, 1, At, B1); PG8_BAR; PG8_SCHED;
;             PG8_LDB(B0, 1, 0); PG8_LDB(B1, 1, 1); PG8_SCHED; PG8_LDA(At, 1, 0); PG8_STAGE(PG8_SA(0, 1), a2 + hstepA, voffA);
;             PG8_WAIT_V(8); PG8_WAIT_L(0); PG8_BAR; PG8_MMA(0, 0, At, B0); PG8_MMA(0, 1, At, B1); PG8_BAR; PG8_SCHED;
	s_waitcnt lgkmcnt(0)
	v_mfma_f32_16x16x32_bf16 v[60:63], v[146:149], v[186:189], v[60:63]
	v_mfma_f32_16x16x32_bf16 v[60:63], v[150:153], v[190:193], v[60:63]
	v_mfma_f32_16x16x32_bf16 v[56:59], v[158:161], v[186:189], v[56:59]
	v_mfma_f32_16x16x32_bf16 v[56:59], v[162:165], v[190:193], v[56:59]
	v_mfma_f32_16x16x32_bf16 v[44:47], v[146:149], v[194:197], v[44:47]
	v_mfma_f32_16x16x32_bf16 v[44:47], v[150:153], v[198:201], v[44:47]
	v_mfma_f32_16x16x32_bf16 v[40:43], v[158:161], v[194:197], v[40:43]
	v_mfma_f32_16x16x32_bf16 v[40:43], v[162:165], v[198:201], v[40:43]
	v_mfma_f32_16x16x32_bf16 v[28:31], v[146:149], v[202:205], v[28:31]
	v_mfma_f32_16x16x32_bf16 v[28:31], v[150:153], v[206:209], v[28:31]
	v_mfma_f32_16x16x32_bf16 v[24:27], v[158:161], v[202:205], v[24:27]
	v_mfma_f32_16x16x32_bf16 v[24:27], v[162:165], v[206:209], v[24:27]
	v_mfma_f32_16x16x32_bf16 v[12:15], v[146:149], v[210:213], v[12:15]
	v_mfma_f32_16x16x32_bf16 v[12:15], v[150:153], v[214:217], v[12:15]
	v_mfma_f32_16x16x32_bf16 v[8:11], v[158:161], v[210:213], v[8:11]
	v_mfma_f32_16x16x32_bf16 v[8:11], v[162:165], v[214:217], v[8:11]
	v_mfma_f32_16x16x32_bf16 v[52:55], v[166:169], v[186:189], v[52:55]
	v_mfma_f32_16x16x32_bf16 v[52:55], v[170:173], v[190:193], v[52:55]
	v_mfma_f32_16x16x32_bf16 v[48:51], v[174:177], v[186:189], v[48:51]
	v_mfma_f32_16x16x32_bf16 v[48:51], v[178:181], v[190:193], v[48:51]
	v_mfma_f32_16x16x32_bf16 v[36:39], v[166:169], v[194:197], v[36:39]
	v_mfma_f32_16x16x32_bf16 v[36:39], v[170:173], v[198:201], v[36:39]
	v_mfma_f32_16x16x32_bf16 v[32:35], v[174:177], v[194:197], v[32:35]
	v_mfma_f32_16x16x32_bf16 v[32:35], v[178:181], v[198:201], v[32:35]
	v_mfma_f32_16x16x32_bf16 v[20:23], v[166:169], v[202:205], v[20:23]
	v_mfma_f32_16x16x32_bf16 v[20:23], v[170:173], v[206:209], v[20:23]
	v_mfma_f32_16x16x32_bf16 v[16:19], v[174:177], v[202:205], v[16:19]
	v_mfma_f32_16x16x32_bf16 v[16:19], v[178:181], v[206:209], v[16:19]
	v_mfma_f32_16x16x32_bf16 v[4:7], v[166:169], v[210:213], v[4:7]
	v_mfma_f32_16x16x32_bf16 v[4:7], v[170:173], v[214:217], v[4:7]
	v_mfma_f32_16x16x32_bf16 v[0:3], v[174:177], v[210:213], v[0:3]
	v_mfma_f32_16x16x32_bf16 v[0:3], v[178:181], v[214:217], v[0:3]
	s_barrier
	ds_read_b128 v[146:149], v143
	ds_read_b128 v[150:153], v143 offset:1024
	ds_read_b128 v[158:161], v143 offset:2048
	ds_read_b128 v[162:165], v143 offset:3072
	ds_read_b128 v[166:169], v144
	ds_read_b128 v[170:173], v144 offset:1024
	ds_read_b128 v[174:177], v144 offset:2048
	ds_read_b128 v[178:181], v144 offset:3072
	s_add_u32 s20, s20, 0x4000
	s_addc_u32 s21, s21, 0
	s_mov_b32 m0, s41
	v_lshl_add_u64 v[182:183], s[20:21], 0, v[128:129]
	ds_read_b128 v[186:189], v142 offset:32768
	ds_read_b128 v[190:193], v142 offset:33792
	ds_read_b128 v[194:197], v142 offset:34816
	ds_read_b128 v[198:201], v142 offset:35840
	ds_read_b128 v[202:205], v142 offset:36864
	ds_read_b128 v[206:209], v142 offset:37888
	ds_read_b128 v[210:213], v142 offset:38912
	ds_read_b128 v[214:217], v142 offset:39936
	global_load_lds_dwordx4 v[182:183], off
	v_lshl_add_u64 v[182:183], s[20:21], 0, v[132:133]
	s_mov_b32 m0, s42
	s_nop 0
	global_load_lds_dwordx4 v[182:183], off
	s_waitcnt vmcnt(8)
	s_waitcnt lgkmcnt(0)
	s_barrier
	s_waitcnt lgkmcnt(0)
	v_mfma_f32_16x16x32_bf16 v[124:127], v[146:149], v[186:189], v[124:127]
	v_mfma_f32_16x16x32_bf16 v[124:127], v[150:153], v[190:193], v[124:127]
	v_mfma_f32_16x16x32_bf16 v[120:123], v[158:161], v[186:189], v[120:123]
	v_mfma_f32_16x16x32_bf16 v[120:123], v[162:165], v[190:193], v[120:123]
	v_mfma_f32_16x16x32_bf16 v[108:111], v[146:149], v[194:197], v[108:111]
	v_mfma_f32_16x16x32_bf16 v[108:111], v[150:153], v[198:201], v[108:111]
	v_mfma_f32_16x16x32_bf16 v[104:107], v[158:161], v[194:197], v[104:107]
	v_mfma_f32_16x16x32_bf16 v[104:107], v[162:165], v[198:201], v[104:107]
	v_mfma_f32_16x16x32_bf16 v[92:95], v[146:149], v[202:205], v[92:95]
	v_mfma_f32_16x16x32_bf16 v[92:95], v[150:153], v[206:209], v[92:95]
	v_mfma_f32_16x16x32_bf16 v[88:91], v[158:161], v[202:205], v[88:91]
	v_mfma_f32_16x16x32_bf16 v[88:91], v[162:165], v[206:209], v[88:91]
	v_mfma_f32_16x16x32_bf16 v[76:79], v[146:149], v[210:213], v[76:79]
	v_mfma_f32_16x16x32_bf16 v[76:79], v[150:153], v[214:217], v[76:79]
	v_mfma_f32_16x16x32_bf16 v[72:75], v[158:161], v[210:213], v[72:75]
	v_mfma_f32_16x16x32_bf16 v[72:75], v[162:165], v[214:217], v[72:75]
	v_mfma_f32_16x16x32_bf16 v[116:119], v[166:169], v[186:189], v[116:119]
	v_mfma_f32_16x16x32_bf16 v[116:119], v[170:173], v[190:193], v[116:119]
	v_mfma_f32_16x16x32_bf16 v[112:115], v[174:177], v[186:189], v[112:115]
	v_mfma_f32_16x16x32_bf16 v[112:115], v[178:181], v[190:193], v[112:115]
	v_mfma_f32_16x16x32_bf16 v[100:103], v[166:169], v[194:197], v[100:103]
	v_mfma_f32_16x16x32_bf16 v[100:103], v[170:173], v[198:201], v[100:103]
	v_mfma_f32_16x16x32_bf16 v[96:99], v[174:177], v[194:197], v[96:99]
	v_mfma_f32_16x16x32_bf16 v[96:99], v[178:181], v[198:201], v[96:99]
	v_mfma_f32_16x16x32_bf16 v[84:87], v[166:169], v[202:205], v[84:87]
	v_mfma_f32_16x16x32_bf16 v[84:87], v[170:173], v[206:209], v[84:87]
	v_mfma_f32_16x16x32_bf16 v[80:83], v[174:177], v[202:205], v[80:83]
	v_mfma_f32_16x16x32_bf16 v[80:83], v[178:181], v[206:209], v[80:83]
	v_mfma_f32_16x16x32_bf16 v[68:71], v[166:169], v[210:213], v[68:71]
	v_mfma_f32_16x16x32_bf16 v[68:71], v[170:173], v[214:217], v[68:71]
	v_mfma_f32_16x16x32_bf16 v[64:67], v[174:177], v[210:213], v[64:67]
	v_mfma_f32_16x16x32_bf16 v[64:67], v[178:181], v[214:217], v[64:67]
	s_barrier
; #define PG8_STAGE(bufoff, gbase, voff) do { _Pragma("unroll") for (int _i = 0; _i < 2; ++_i) \
;         __builtin_amdgcn_global_load_lds((const unsigned*)((const char*)(gbase) + (voff)[_i]), (LAS unsigned*)(lds + (bufoff) + ldsw + _i * 8192), 16, 0, 0); } while (0)
; #define PG8_LDA(dst, b, h) do { _Pragma("unroll") for (int m = 0; m < 4; ++m) _Pragma("unroll") for (int k = 0; k < 2; ++k) dst[m][k] = *(const LAS bf16x8*)(lds + PG8_SA(b, h) + aoff + m * 2048 + k * 1024); } while (0)
; #define PG8_MMA(ai, bj, At, Bt) do { __builtin_amdgcn_s_setprio(1); _Pragma("unroll") for (int m = 0; m < 4; ++m) _Pragma("unroll") for (int n = 0; n < 2; ++n) _Pragma("unroll") for (int k = 0; k < 2; ++k) \
;         acc[ai][bj][m][n] = __builtin_amdgcn_mfma_f32_16x16x32_bf16(Bt[n][k], At[m][k], acc[ai][bj][m][n], 0, 0, 0); __builtin_amdgcn_s_setprio(0); } while (0)
; #define PG8_WAIT_V(n) asm volatile("s_waitcnt vmcnt(" #n ")" ::: "memory")
; #define PG8_WAIT_L(n) asm volatile("s_waitcnt lgkmcnt(" #n ")" ::: "memory")
; #define PG8_BAR __builtin_amdgcn_s_barrier()
; #define PG8_SCHED __builtin_amdgcn_sched_barrier(0)
; template <bool ALIGN_EPI, class Epi, class Sched>
; __device__ __forceinline__ void gemm_phase(LAS unsigned char* lds, const int lda, const int ldb, const int K, const Sched& S, const Epi& E, const size_t kstepA = (size_t)(BK * 2), const size_t kstepB = (size_t)(BK * 2)) {
;     ...
;             PG8_LDA(At, 1, 1); PG8_STAGE(PG8_SB(1, 0), b3, voffB); PG8_STAGE(PG8_SB(1, 1), b3 + hstepB, voffB); PG8_STAGE(PG8_SA(1, 0), a3, voffA);
;             PG8_WAIT_V(8); PG8_WAIT_L(0); PG8_BAR; PG8_MMA(1, 0, At, B0); PG8_MMA(1, 1, At, B1); PG8_BAR; PG8_SCHED;
;         }
;     ...
;     PG8_WAIT_V(0);
;     if constexpr (!ALIGN_EPI) { if (wr == 0) PG8_BAR; }
	s_add_u32 s20, s16, 0x20000
	s_addc_u32 s21, s17, 0
	s_mov_b32 m0, s56
	v_lshl_add_u64 v[182:183], s[20:21], 0, v[130:131]
	s_add_u32 s16, s16, 0x24000
	ds_read_b128 v[186:189], v142 offset:49152
	ds_read_b128 v[190:193], v142 offset:50176
	ds_read_b128 v[194:197], v142 offset:51200
	ds_read_b128 v[198:201], v142 offset:52224
	ds_read_b128 v[202:205], v142 offset:53248
	ds_read_b128 v[206:209], v142 offset:54272
	ds_read_b128 v[210:213], v142 offset:55296
	ds_read_b128 v[214:217], v142 offset:56320
	global_load_lds_dwordx4 v[182:183], off
	v_lshl_add_u64 v[182:183], s[20:21], 0, v[134:135]
	s_mov_b32 m0, s57
	s_addc_u32 s17, s17, 0
	global_load_lds_dwordx4 v[182:183], off
	v_lshl_add_u64 v[182:183], s[16:17], 0, v[130:131]
	s_mov_b32 m0, s58
	s_nop 0
	global_load_lds_dwordx4 v[182:183], off
	v_lshl_add_u64 v[182:183], s[16:17], 0, v[134:135]
	s_mov_b32 m0, s59
	s_nop 0
	global_load_lds_dwordx4 v[182:183], off
	v_lshl_add_u64 v[182:183], s[14:15], 0, v[128:129]
	s_mov_b32 m0, s43
	s_nop 0
	global_load_lds_dwordx4 v[182:183], off
	v_lshl_add_u64 v[182:183], s[14:15], 0, v[132:133]
	s_mov_b32 m0, s44
	s_nop 0
	global_load_lds_dwordx4 v[182:183], off
	s_waitcnt vmcnt(8)
	s_waitcnt lgkmcnt(0)
	s_barrier
	s_waitcnt lgkmcnt(0)
	v_mfma_f32_16x16x32_bf16 v[60:63], v[146:149], v[186:189], v[60:63]
	v_mfma_f32_16x16x32_bf16 v[60:63], v[150:153], v[190:193], v[60:63]
	v_mfma_f32_16x16x32_bf16 v[56:59], v[158:161], v[186:189], v[56:59]
	v_mfma_f32_16x16x32_bf16 v[56:59], v[162:165], v[190:193], v[56:59]
	v_mfma_f32_16x16x32_bf16 v[44:47], v[146:149], v[194:197], v[44:47]
	v_mfma_f32_16x16x32_bf16 v[44:47], v[150:153], v[198:201], v[44:47]
	v_mfma_f32_16x16x32_bf16 v[40:43], v[158:161], v[194:197], v[40:43]
	v_mfma_f32_16x16x32_bf16 v[40:43], v[162:165], v[198:201], v[40:43]
	v_mfma_f32_16x16x32_bf16 v[28:31], v[146:149], v[202:205], v[28:31]
	v_mfma_f32_16x16x32_bf16 v[28:31], v[150:153], v[206:209], v[28:31]
	v_mfma_f32_16x16x32_bf16 v[24:27], v[158:161], v[202:205], v[24:27]
	v_mfma_f32_16x16x32_bf16 v[24:27], v[162:165], v[206:209], v[24:27]
	v_mfma_f32_16x16x32_bf16 v[12:15], v[146:149], v[210:213], v[12:15]
	v_mfma_f32_16x16x32_bf16 v[12:15], v[150:153], v[214:217], v[12:15]
	v_mfma_f32_16x16x32_bf16 v[8:11], v[158:161], v[210:213], v[8:11]
	v_mfma_f32_16x16x32_bf16 v[8:11], v[162:165], v[214:217], v[8:11]
	v_mfma_f32_16x16x32_bf16 v[52:55], v[166:169], v[186:189], v[52:55]
	v_mfma_f32_16x16x32_bf16 v[52:55], v[170:173], v[190:193], v[52:55]
	v_mfma_f32_16x16x32_bf16 v[48:51], v[174:177], v[186:189], v[48:51]
	v_mfma_f32_16x16x32_bf16 v[48:51], v[178:181], v[190:193], v[48:51]
	v_mfma_f32_16x16x32_bf16 v[36:39], v[166:169], v[194:197], v[36:39]
	v_mfma_f32_16x16x32_bf16 v[36:39], v[170:173], v[198:201], v[36:39]
	v_mfma_f32_16x16x32_bf16 v[32:35], v[174:177], v[194:197], v[32:35]
	v_mfma_f32_16x16x32_bf16 v[32:35], v[178:181], v[198:201], v[32:35]
	v_mfma_f32_16x16x32_bf16 v[20:23], v[166:169], v[202:205], v[20:23]
	v_mfma_f32_16x16x32_bf16 v[20:23], v[170:173], v[206:209], v[20:23]
	v_mfma_f32_16x16x32_bf16 v[16:19], v[174:177], v[202:205], v[16:19]
	v_mfma_f32_16x16x32_bf16 v[16:19], v[178:181], v[206:209], v[16:19]
	v_mfma_f32_16x16x32_bf16 v[4:7], v[166:169], v[210:213], v[4:7]
	v_mfma_f32_16x16x32_bf16 v[4:7], v[170:173], v[214:217], v[4:7]
	v_mfma_f32_16x16x32_bf16 v[0:3], v[174:177], v[210:213], v[0:3]
	v_mfma_f32_16x16x32_bf16 v[0:3], v[178:181], v[214:217], v[0:3]
	s_barrier
	s_add_i32 s49, s49, 2
	s_add_u32 s45, s45, 0x40000
	s_addc_u32 s48, s48, 0
	s_add_u32 s12, s12, 0x400000
	s_addc_u32 s13, s13, 0
	v_lshl_add_u64 v[136:137], v[136:137], 0, s[6:7]
	s_cmp_lt_u32 s49, 30
	v_lshl_add_u64 v[138:139], v[138:139], 0, s[6:7]
	s_cbranch_scc1 .LBB0_813
	s_waitcnt vmcnt(0)
	s_cmpk_gt_u32 s23, 0xff
	s_cbranch_scc1 .LBB0_816
	s_barrier
